# stacked: no s_setprio flips + counted-wait EpiGate + restore barrier behind unit header + P8 de-renaming + peel + trim15
# speedup vs baseline: 1.0025x; 1.0025x over previous
; #define PG8_STAGE(bufoff, gbase, voff) do { _Pragma("unroll") for (int _i = 0; _i < 2; ++_i) \
;         __builtin_amdgcn_global_load_lds((const unsigned*)((const char*)(gbase) + (voff)[_i]), (PG8_LAS unsigned*)(lds + (bufoff) + ldsw + _i * 8192), 16, 0, 0); } while (0)
; #define PG8_LDA(dst, b, h) do { _Pragma("unroll") for (int m = 0; m < 4; ++m) _Pragma("unroll") for (int k = 0; k < 2; ++k) dst[m][k] = *(const PG8_LAS bf16x8*)(lds + PG8_SA(b, h) + aoff + m * 2048 + k * 1024); } while (0)
; #define PG8_LDB(dst, b, h) do { _Pragma("unroll") for (int n = 0; n < 2; ++n) _Pragma("unroll") for (int k = 0; k < 2; ++k) dst[n][k] = *(const PG8_LAS bf16x8*)(lds + PG8_SB(b, h) + boff + n * 2048 + k * 1024); } while (0)
; #define PG8_MMA(ai, bj, At, Bt) do { __builtin_amdgcn_s_setprio(1); _Pragma("unroll") for (int m = 0; m < 4; ++m) _Pragma("unroll") for (int n = 0; n < 2; ++n) _Pragma("unroll") for (int k = 0; k < 2; ++k) \
;         acc[ai][bj][m][n] = __builtin_amdgcn_mfma_f32_16x16x32_bf16(Bt[n][k], At[m][k], acc[ai][bj][m][n], 0, 0, 0); __builtin_amdgcn_s_setprio(0); } while (0)
; #define PG8_WAIT_V(n) asm volatile("s_waitcnt vmcnt(" #n ")" ::: "memory")
; #define PG8_WAIT_L(n) asm volatile("s_waitcnt lgkmcnt(" #n ")" ::: "memory")
; template <class Epi, class Sched, bool ALIGN_EPI = false, bool SP2 = false>
; __device__ __forceinline__ void gemm_phase(PG8_LAS unsigned char* lds, const Gemm g, const Sched& S, const Epi& E) {
;     ...
;             const bool last = (t == nt - 2);
;             const char* a1 = cA + (size_t)(t + 1) * kstep;
;             const char* a2 = last ? nA : cA + (size_t)(t + 2) * kstep; const char* b2 = last ? nB : cB + (size_t)(t + 2) * kstep;
;             const char* a3 = a2 + kstep; const char* b3 = b2 + kstep;
;             if (last && has_next) S.a_ready(nxt);
;             if constexpr (SP2) {
;             PG8_LDB(B0, 0, 0); PG8_LDB(B1, 0, 1); PG8_SCHED; PG8_LDA(At, 0, 0); PG8_STAGE(PG8_SA(1, 1), a1 + hstep, voffA);
;             PG8_WAIT_V(8); PG8_WAIT_L(0); PG8_BAR; PG8_MMA(0, 0, At, B0); PG8_MMA(0, 1, At, B1); PG8_BAR; PG8_SCHED;
;             PG8_LDA(At, 0, 1); PG8_STAGE(PG8_SB(0, 0), b2, voffB); PG8_STAGE(PG8_SB(0, 1), b2 + hstep, voffB); PG8_STAGE(PG8_SA(0, 0), a2, voffA);
;             PG8_WAIT_V(8); PG8_WAIT_L(0); PG8_BAR; PG8_MMA(1, 0, At, B0); PG8_MMA(1, 1, At, B1); PG8_BAR; PG8_SCHED;
.Lrb_skip_0:
	s_add_u32 s26, s62, 0xfff00080
	s_addc_u32 s27, s63, -1
	s_add_i32 s65, 0, 0x10000
	s_cmp_eq_u32 s17, 60
	s_cselect_b32 s29, s30, s27
	s_cselect_b32 s28, s31, s26
	v_add_u32_e32 v170, s65, v182
	s_cselect_b32 s27, s53, s16
	s_cselect_b32 s26, s55, vcc_lo
	s_add_i32 s70, 0, 0x14000
	ds_read_b128 v[122:125], v170
	ds_read_b128 v[126:129], v170 offset:1024
	ds_read_b128 v[130:133], v170 offset:2048
	ds_read_b128 v[172:175], v170 offset:3072
	v_add_u32_e32 v170, s70, v182
	ds_read_b128 v[176:179], v170
	ds_read_b128 v[192:195], v170 offset:1024
	ds_read_b128 v[196:199], v170 offset:2048
	ds_read_b128 v[200:203], v170 offset:3072
	v_lshl_add_u64 v[180:181], s[62:63], 0, v[156:157]
	s_add_i32 m0, s10, 0xc000
	ds_read_b128 v[204:207], v191
	ds_read_b128 v[220:223], v191 offset:1024
	ds_read_b128 v[224:227], v191 offset:2048
	ds_read_b128 v[228:231], v191 offset:3072
	ds_read_b128 v[232:235], v191 offset:4096
	ds_read_b128 v[236:239], v191 offset:5120
	ds_read_b128 v[240:243], v191 offset:6144
	ds_read_b128 v[244:247], v191 offset:7168
	global_load_lds_dwordx4 v[180:181], off
	v_lshl_add_u64 v[180:181], s[62:63], 0, v[154:155]
	s_add_i32 m0, s10, 0xe000
	s_nop 0
	global_load_lds_dwordx4 v[180:181], off
	s_waitcnt vmcnt(8)
	s_waitcnt lgkmcnt(0)
	s_barrier
	v_mfma_f32_16x16x32_bf16 v[118:121], v[122:125], v[204:207], 0
	v_mfma_f32_16x16x32_bf16 v[138:141], v[130:133], v[204:207], 0
	v_mfma_f32_16x16x32_bf16 v[102:105], v[122:125], v[224:227], 0
	v_mfma_f32_16x16x32_bf16 v[114:117], v[130:133], v[224:227], 0
	v_mfma_f32_16x16x32_bf16 v[86:89], v[122:125], v[232:235], 0
	v_mfma_f32_16x16x32_bf16 v[98:101], v[130:133], v[232:235], 0
	v_mfma_f32_16x16x32_bf16 v[70:73], v[122:125], v[240:243], 0
	v_mfma_f32_16x16x32_bf16 v[82:85], v[130:133], v[240:243], 0
	v_mfma_f32_16x16x32_bf16 v[118:121], v[126:129], v[220:223], v[118:121]
	v_mfma_f32_16x16x32_bf16 v[138:141], v[172:175], v[220:223], v[138:141]
	v_mfma_f32_16x16x32_bf16 v[102:105], v[126:129], v[228:231], v[102:105]
	v_mfma_f32_16x16x32_bf16 v[114:117], v[172:175], v[228:231], v[114:117]
	v_mfma_f32_16x16x32_bf16 v[86:89], v[126:129], v[236:239], v[86:89]
	v_mfma_f32_16x16x32_bf16 v[98:101], v[172:175], v[236:239], v[98:101]
	v_mfma_f32_16x16x32_bf16 v[70:73], v[126:129], v[244:247], v[70:73]
	v_mfma_f32_16x16x32_bf16 v[82:85], v[172:175], v[244:247], v[82:85]
	v_mfma_f32_16x16x32_bf16 v[134:137], v[176:179], v[204:207], 0
	v_mfma_f32_16x16x32_bf16 v[110:113], v[196:199], v[204:207], 0
	v_mfma_f32_16x16x32_bf16 v[106:109], v[176:179], v[224:227], 0
	v_mfma_f32_16x16x32_bf16 v[94:97], v[196:199], v[224:227], 0
	v_mfma_f32_16x16x32_bf16 v[90:93], v[176:179], v[232:235], 0
	v_mfma_f32_16x16x32_bf16 v[78:81], v[196:199], v[232:235], 0
	v_mfma_f32_16x16x32_bf16 v[74:77], v[176:179], v[240:243], 0
	v_mfma_f32_16x16x32_bf16 v[66:69], v[196:199], v[240:243], 0
	v_mfma_f32_16x16x32_bf16 v[134:137], v[192:195], v[220:223], v[134:137]
	v_mfma_f32_16x16x32_bf16 v[110:113], v[200:203], v[220:223], v[110:113]
	v_mfma_f32_16x16x32_bf16 v[106:109], v[192:195], v[228:231], v[106:109]
	v_mfma_f32_16x16x32_bf16 v[94:97], v[200:203], v[228:231], v[94:97]
	v_mfma_f32_16x16x32_bf16 v[90:93], v[192:195], v[236:239], v[90:93]
	v_mfma_f32_16x16x32_bf16 v[78:81], v[200:203], v[236:239], v[78:81]
	v_mfma_f32_16x16x32_bf16 v[74:77], v[192:195], v[244:247], v[74:77]
	v_mfma_f32_16x16x32_bf16 v[66:69], v[200:203], v[244:247], v[66:69]
	s_barrier
	s_add_i32 s65, s65, s9
	v_lshl_add_u64 v[180:181], s[26:27], 0, v[158:159]
	s_mov_b32 m0, s65
	ds_read_b128 v[204:207], v191 offset:16384
	ds_read_b128 v[220:223], v191 offset:17408
	ds_read_b128 v[224:227], v191 offset:18432
	ds_read_b128 v[228:231], v191 offset:19456
	ds_read_b128 v[232:235], v191 offset:20480
	ds_read_b128 v[236:239], v191 offset:21504
	ds_read_b128 v[240:243], v191 offset:22528
	ds_read_b128 v[244:247], v191 offset:23552
	global_load_lds_dwordx4 v[180:181], off
	s_add_i32 m0, s65, 0x2000
	s_add_u32 s68, s26, 0x100000
	v_lshl_add_u64 v[208:209], s[26:27], 0, v[142:143]
	s_addc_u32 s69, s27, 0
	s_add_i32 s65, s70, s9
	global_load_lds_dwordx4 v[208:209], off
	v_lshl_add_u64 v[248:249], s[68:69], 0, v[158:159]
	s_mov_b32 m0, s65
	v_lshl_add_u64 v[170:171], s[28:29], 0, v[144:145]
	global_load_lds_dwordx4 v[248:249], off
	v_lshl_add_u64 v[248:249], s[68:69], 0, v[142:143]
	s_add_i32 m0, s65, 0x2000
	s_nop 0
	global_load_lds_dwordx4 v[248:249], off
	v_lshl_add_u64 v[248:249], s[28:29], 0, v[146:147]
	s_mov_b32 m0, s10
	s_nop 0
	global_load_lds_dwordx4 v[248:249], off
	s_mov_b32 m0, s11
	s_nop 0
	global_load_lds_dwordx4 v[170:171], off
	s_waitcnt vmcnt(8)
	s_waitcnt lgkmcnt(0)
	s_barrier
; #define PG8_STAGE(bufoff, gbase, voff) do { _Pragma("unroll") for (int _i = 0; _i < 2; ++_i) \
;         __builtin_amdgcn_global_load_lds((const unsigned*)((const char*)(gbase) + (voff)[_i]), (PG8_LAS unsigned*)(lds + (bufoff) + ldsw + _i * 8192), 16, 0, 0); } while (0)
; #define PG8_LDA(dst, b, h) do { _Pragma("unroll") for (int m = 0; m < 4; ++m) _Pragma("unroll") for (int k = 0; k < 2; ++k) dst[m][k] = *(const PG8_LAS bf16x8*)(lds + PG8_SA(b, h) + aoff + m * 2048 + k * 1024); } while (0)
; #define PG8_LDB(dst, b, h) do { _Pragma("unroll") for (int n = 0; n < 2; ++n) _Pragma("unroll") for (int k = 0; k < 2; ++k) dst[n][k] = *(const PG8_LAS bf16x8*)(lds + PG8_SB(b, h) + boff + n * 2048 + k * 1024); } while (0)
; #define PG8_MMA(ai, bj, At, Bt) do { __builtin_amdgcn_s_setprio(1); _Pragma("unroll") for (int m = 0; m < 4; ++m) _Pragma("unroll") for (int n = 0; n < 2; ++n) _Pragma("unroll") for (int k = 0; k < 2; ++k) \
;         acc[ai][bj][m][n] = __builtin_amdgcn_mfma_f32_16x16x32_bf16(Bt[n][k], At[m][k], acc[ai][bj][m][n], 0, 0, 0); __builtin_amdgcn_s_setprio(0); } while (0)
; #define PG8_WAIT_V(n) asm volatile("s_waitcnt vmcnt(" #n ")" ::: "memory")
; #define PG8_WAIT_L(n) asm volatile("s_waitcnt lgkmcnt(" #n ")" ::: "memory")
; #define PG8_BAR __builtin_amdgcn_s_barrier()
; #define PG8_SCHED __builtin_amdgcn_sched_barrier(0)
; template <class Epi, class Sched, bool ALIGN_EPI = false, bool SP2 = false>
; __device__ __forceinline__ void gemm_phase(PG8_LAS unsigned char* lds, const Gemm g, const Sched& S, const Epi& E) {
;     ...
;             PG8_WAIT_V(8); PG8_WAIT_L(0); PG8_BAR; PG8_MMA(1, 0, At, B0); PG8_MMA(1, 1, At, B1); PG8_BAR; PG8_SCHED;
;             PG8_LDB(B0, 1, 0); PG8_LDB(B1, 1, 1); PG8_SCHED; PG8_LDA(At, 1, 0); PG8_STAGE(PG8_SA(0, 1), a2 + hstep, voffA);
;             PG8_WAIT_V(8); PG8_WAIT_L(0); PG8_BAR; PG8_MMA(0, 0, At, B0); PG8_MMA(0, 1, At, B1); PG8_BAR; PG8_SCHED;
	v_mfma_f32_16x16x32_bf16 v[54:57], v[122:125], v[204:207], 0
	v_mfma_f32_16x16x32_bf16 v[62:65], v[130:133], v[204:207], 0
	v_mfma_f32_16x16x32_bf16 v[38:41], v[122:125], v[224:227], 0
	v_mfma_f32_16x16x32_bf16 v[50:53], v[130:133], v[224:227], 0
	v_mfma_f32_16x16x32_bf16 v[22:25], v[122:125], v[232:235], 0
	v_mfma_f32_16x16x32_bf16 v[34:37], v[130:133], v[232:235], 0
	v_mfma_f32_16x16x32_bf16 v[6:9], v[122:125], v[240:243], 0
	v_mfma_f32_16x16x32_bf16 v[18:21], v[130:133], v[240:243], 0
	v_mfma_f32_16x16x32_bf16 v[54:57], v[126:129], v[220:223], v[54:57]
	v_mfma_f32_16x16x32_bf16 v[62:65], v[172:175], v[220:223], v[62:65]
	v_mfma_f32_16x16x32_bf16 v[38:41], v[126:129], v[228:231], v[38:41]
	v_mfma_f32_16x16x32_bf16 v[50:53], v[172:175], v[228:231], v[50:53]
	v_mfma_f32_16x16x32_bf16 v[22:25], v[126:129], v[236:239], v[22:25]
	v_mfma_f32_16x16x32_bf16 v[34:37], v[172:175], v[236:239], v[34:37]
	v_mfma_f32_16x16x32_bf16 v[6:9], v[126:129], v[244:247], v[6:9]
	v_mfma_f32_16x16x32_bf16 v[18:21], v[172:175], v[244:247], v[18:21]
	v_mfma_f32_16x16x32_bf16 v[58:61], v[176:179], v[204:207], 0
	v_mfma_f32_16x16x32_bf16 v[46:49], v[196:199], v[204:207], 0
	v_mfma_f32_16x16x32_bf16 v[42:45], v[176:179], v[224:227], 0
	v_mfma_f32_16x16x32_bf16 v[30:33], v[196:199], v[224:227], 0
	v_mfma_f32_16x16x32_bf16 v[26:29], v[176:179], v[232:235], 0
	v_mfma_f32_16x16x32_bf16 v[14:17], v[196:199], v[232:235], 0
	v_mfma_f32_16x16x32_bf16 v[10:13], v[176:179], v[240:243], 0
	v_mfma_f32_16x16x32_bf16 v[2:5], v[196:199], v[240:243], 0
	v_mfma_f32_16x16x32_bf16 v[58:61], v[192:195], v[220:223], v[58:61]
	v_mfma_f32_16x16x32_bf16 v[46:49], v[200:203], v[220:223], v[46:49]
	v_mfma_f32_16x16x32_bf16 v[42:45], v[192:195], v[228:231], v[42:45]
	v_mfma_f32_16x16x32_bf16 v[30:33], v[200:203], v[228:231], v[30:33]
	v_mfma_f32_16x16x32_bf16 v[26:29], v[192:195], v[236:239], v[26:29]
	v_mfma_f32_16x16x32_bf16 v[14:17], v[200:203], v[236:239], v[14:17]
	v_mfma_f32_16x16x32_bf16 v[10:13], v[192:195], v[244:247], v[10:13]
	v_mfma_f32_16x16x32_bf16 v[2:5], v[200:203], v[244:247], v[2:5]
	s_barrier
	s_add_i32 s65, 0, 0x18000
	s_add_i32 s68, 0, 0x1c000
	v_add_u32_e32 v172, s65, v182
	v_add_u32_e32 v200, s68, v182
	ds_read_b128 v[122:125], v172
	ds_read_b128 v[126:129], v172 offset:1024
	ds_read_b128 v[130:133], v172 offset:2048
	ds_read_b128 v[172:175], v172 offset:3072
	ds_read_b128 v[176:179], v200
	ds_read_b128 v[192:195], v200 offset:1024
	ds_read_b128 v[196:199], v200 offset:2048
	ds_read_b128 v[200:203], v200 offset:3072
	s_add_u32 s28, s28, 0x100000
	s_addc_u32 s29, s29, 0
	s_mov_b32 m0, s12
	v_lshl_add_u64 v[210:211], s[28:29], 0, v[146:147]
	ds_read_b128 v[204:207], v191 offset:32768
	ds_read_b128 v[220:223], v191 offset:33792
	ds_read_b128 v[224:227], v191 offset:34816
	ds_read_b128 v[228:231], v191 offset:35840
	ds_read_b128 v[232:235], v191 offset:36864
	ds_read_b128 v[236:239], v191 offset:37888
	ds_read_b128 v[240:243], v191 offset:38912
	ds_read_b128 v[244:247], v191 offset:39936
	global_load_lds_dwordx4 v[210:211], off
	v_lshl_add_u64 v[210:211], s[28:29], 0, v[144:145]
	s_mov_b32 m0, s13
	s_nop 0
	global_load_lds_dwordx4 v[210:211], off
	s_waitcnt vmcnt(8)
	s_waitcnt lgkmcnt(0)
	s_barrier
	v_mfma_f32_16x16x32_bf16 v[118:121], v[122:125], v[204:207], v[118:121]
	v_mfma_f32_16x16x32_bf16 v[138:141], v[130:133], v[204:207], v[138:141]
	v_mfma_f32_16x16x32_bf16 v[102:105], v[122:125], v[224:227], v[102:105]
	v_mfma_f32_16x16x32_bf16 v[114:117], v[130:133], v[224:227], v[114:117]
	v_mfma_f32_16x16x32_bf16 v[86:89], v[122:125], v[232:235], v[86:89]
	v_mfma_f32_16x16x32_bf16 v[98:101], v[130:133], v[232:235], v[98:101]
	v_mfma_f32_16x16x32_bf16 v[70:73], v[122:125], v[240:243], v[70:73]
	v_mfma_f32_16x16x32_bf16 v[82:85], v[130:133], v[240:243], v[82:85]
	v_mfma_f32_16x16x32_bf16 v[118:121], v[126:129], v[220:223], v[118:121]
	v_mfma_f32_16x16x32_bf16 v[138:141], v[172:175], v[220:223], v[138:141]
	v_mfma_f32_16x16x32_bf16 v[102:105], v[126:129], v[228:231], v[102:105]
	v_mfma_f32_16x16x32_bf16 v[114:117], v[172:175], v[228:231], v[114:117]
	v_mfma_f32_16x16x32_bf16 v[86:89], v[126:129], v[236:239], v[86:89]
	v_mfma_f32_16x16x32_bf16 v[98:101], v[172:175], v[236:239], v[98:101]
	v_mfma_f32_16x16x32_bf16 v[70:73], v[126:129], v[244:247], v[70:73]
	v_mfma_f32_16x16x32_bf16 v[82:85], v[172:175], v[244:247], v[82:85]
	v_mfma_f32_16x16x32_bf16 v[134:137], v[176:179], v[204:207], v[134:137]
	v_mfma_f32_16x16x32_bf16 v[110:113], v[196:199], v[204:207], v[110:113]
	v_mfma_f32_16x16x32_bf16 v[106:109], v[176:179], v[224:227], v[106:109]
	v_mfma_f32_16x16x32_bf16 v[94:97], v[196:199], v[224:227], v[94:97]
	v_mfma_f32_16x16x32_bf16 v[90:93], v[176:179], v[232:235], v[90:93]
	v_mfma_f32_16x16x32_bf16 v[78:81], v[196:199], v[232:235], v[78:81]
	v_mfma_f32_16x16x32_bf16 v[74:77], v[176:179], v[240:243], v[74:77]
	v_mfma_f32_16x16x32_bf16 v[66:69], v[196:199], v[240:243], v[66:69]
	v_mfma_f32_16x16x32_bf16 v[134:137], v[192:195], v[220:223], v[134:137]
	v_mfma_f32_16x16x32_bf16 v[110:113], v[200:203], v[220:223], v[110:113]
	v_mfma_f32_16x16x32_bf16 v[106:109], v[192:195], v[228:231], v[106:109]
	v_mfma_f32_16x16x32_bf16 v[94:97], v[200:203], v[228:231], v[94:97]
	v_mfma_f32_16x16x32_bf16 v[90:93], v[192:195], v[236:239], v[90:93]
	v_mfma_f32_16x16x32_bf16 v[78:81], v[200:203], v[236:239], v[78:81]
	v_mfma_f32_16x16x32_bf16 v[74:77], v[192:195], v[244:247], v[74:77]
	v_mfma_f32_16x16x32_bf16 v[66:69], v[200:203], v[244:247], v[66:69]
	s_barrier
; #define PG8_STAGE(bufoff, gbase, voff) do { _Pragma("unroll") for (int _i = 0; _i < 2; ++_i) \
;         __builtin_amdgcn_global_load_lds((const unsigned*)((const char*)(gbase) + (voff)[_i]), (PG8_LAS unsigned*)(lds + (bufoff) + ldsw + _i * 8192), 16, 0, 0); } while (0)
; #define PG8_LDA(dst, b, h) do { _Pragma("unroll") for (int m = 0; m < 4; ++m) _Pragma("unroll") for (int k = 0; k < 2; ++k) dst[m][k] = *(const PG8_LAS bf16x8*)(lds + PG8_SA(b, h) + aoff + m * 2048 + k * 1024); } while (0)
; #define PG8_MMA(ai, bj, At, Bt) do { __builtin_amdgcn_s_setprio(1); _Pragma("unroll") for (int m = 0; m < 4; ++m) _Pragma("unroll") for (int n = 0; n < 2; ++n) _Pragma("unroll") for (int k = 0; k < 2; ++k) \
;         acc[ai][bj][m][n] = __builtin_amdgcn_mfma_f32_16x16x32_bf16(Bt[n][k], At[m][k], acc[ai][bj][m][n], 0, 0, 0); __builtin_amdgcn_s_setprio(0); } while (0)
; #define PG8_WAIT_V(n) asm volatile("s_waitcnt vmcnt(" #n ")" ::: "memory")
; #define PG8_WAIT_L(n) asm volatile("s_waitcnt lgkmcnt(" #n ")" ::: "memory")
; #define PG8_BAR __builtin_amdgcn_s_barrier()
; #define PG8_SCHED __builtin_amdgcn_sched_barrier(0)
; template <class Epi, class Sched, bool ALIGN_EPI = false, bool SP2 = false>
; __device__ __forceinline__ void gemm_phase(PG8_LAS unsigned char* lds, const Gemm g, const Sched& S, const Epi& E) {
;     ...
;             PG8_LDA(At, 1, 1); PG8_STAGE(PG8_SB(1, 0), b3, voffB); PG8_STAGE(PG8_SB(1, 1), b3 + hstep, voffB); PG8_STAGE(PG8_SA(1, 0), a3, voffA);
;             PG8_WAIT_V(8); PG8_WAIT_L(0); PG8_BAR; PG8_MMA(1, 0, At, B0); PG8_MMA(1, 1, At, B1); PG8_BAR; PG8_SCHED;
	s_add_i32 s28, s65, s9
	v_lshl_add_u64 v[180:181], v[180:181], 0, s[96:97]
	s_mov_b32 m0, s28
	ds_read_b128 v[204:207], v191 offset:49152
	ds_read_b128 v[220:223], v191 offset:50176
	ds_read_b128 v[224:227], v191 offset:51200
	ds_read_b128 v[228:231], v191 offset:52224
	ds_read_b128 v[232:235], v191 offset:53248
	ds_read_b128 v[236:239], v191 offset:54272
	ds_read_b128 v[240:243], v191 offset:55296
	ds_read_b128 v[244:247], v191 offset:56320
	global_load_lds_dwordx4 v[180:181], off
	s_add_i32 m0, s28, 0x2000
	s_add_u32 s26, s26, 0x100080
	v_lshl_add_u64 v[180:181], v[208:209], 0, s[96:97]
	s_addc_u32 s27, s27, 0
	s_add_i32 s28, s68, s9
	global_load_lds_dwordx4 v[180:181], off
	v_lshl_add_u64 v[180:181], s[26:27], 0, v[158:159]
	s_mov_b32 m0, s28
	v_lshl_add_u64 v[170:171], v[170:171], 0, s[96:97]
	global_load_lds_dwordx4 v[180:181], off
	v_lshl_add_u64 v[180:181], s[26:27], 0, v[142:143]
	s_add_i32 m0, s28, 0x2000
	s_nop 0
	global_load_lds_dwordx4 v[180:181], off
	v_lshl_add_u64 v[180:181], v[248:249], 0, s[96:97]
	s_mov_b32 m0, s0
	s_nop 0
	global_load_lds_dwordx4 v[180:181], off
	s_mov_b32 m0, s34
	s_nop 0
	global_load_lds_dwordx4 v[170:171], off
	s_waitcnt vmcnt(8)
	s_waitcnt lgkmcnt(0)
	s_barrier
	v_mfma_f32_16x16x32_bf16 v[54:57], v[122:125], v[204:207], v[54:57]
	v_mfma_f32_16x16x32_bf16 v[62:65], v[130:133], v[204:207], v[62:65]
	v_mfma_f32_16x16x32_bf16 v[38:41], v[122:125], v[224:227], v[38:41]
	v_mfma_f32_16x16x32_bf16 v[50:53], v[130:133], v[224:227], v[50:53]
	v_mfma_f32_16x16x32_bf16 v[22:25], v[122:125], v[232:235], v[22:25]
	v_mfma_f32_16x16x32_bf16 v[34:37], v[130:133], v[232:235], v[34:37]
	v_mfma_f32_16x16x32_bf16 v[6:9], v[122:125], v[240:243], v[6:9]
	v_mfma_f32_16x16x32_bf16 v[18:21], v[130:133], v[240:243], v[18:21]
	v_mfma_f32_16x16x32_bf16 v[54:57], v[126:129], v[220:223], v[54:57]
	v_mfma_f32_16x16x32_bf16 v[62:65], v[172:175], v[220:223], v[62:65]
	v_mfma_f32_16x16x32_bf16 v[38:41], v[126:129], v[228:231], v[38:41]
	v_mfma_f32_16x16x32_bf16 v[50:53], v[172:175], v[228:231], v[50:53]
	v_mfma_f32_16x16x32_bf16 v[22:25], v[126:129], v[236:239], v[22:25]
	v_mfma_f32_16x16x32_bf16 v[34:37], v[172:175], v[236:239], v[34:37]
	v_mfma_f32_16x16x32_bf16 v[6:9], v[126:129], v[244:247], v[6:9]
	v_mfma_f32_16x16x32_bf16 v[18:21], v[172:175], v[244:247], v[18:21]
	v_mfma_f32_16x16x32_bf16 v[58:61], v[176:179], v[204:207], v[58:61]
	v_mfma_f32_16x16x32_bf16 v[46:49], v[196:199], v[204:207], v[46:49]
	v_mfma_f32_16x16x32_bf16 v[42:45], v[176:179], v[224:227], v[42:45]
	v_mfma_f32_16x16x32_bf16 v[30:33], v[196:199], v[224:227], v[30:33]
	v_mfma_f32_16x16x32_bf16 v[26:29], v[176:179], v[232:235], v[26:29]
	v_mfma_f32_16x16x32_bf16 v[14:17], v[196:199], v[232:235], v[14:17]
	v_mfma_f32_16x16x32_bf16 v[10:13], v[176:179], v[240:243], v[10:13]
	v_mfma_f32_16x16x32_bf16 v[2:5], v[196:199], v[240:243], v[2:5]
	v_mfma_f32_16x16x32_bf16 v[58:61], v[192:195], v[220:223], v[58:61]
	v_mfma_f32_16x16x32_bf16 v[46:49], v[200:203], v[220:223], v[46:49]
	v_mfma_f32_16x16x32_bf16 v[42:45], v[192:195], v[228:231], v[42:45]
	v_mfma_f32_16x16x32_bf16 v[30:33], v[200:203], v[228:231], v[30:33]
	v_mfma_f32_16x16x32_bf16 v[26:29], v[192:195], v[236:239], v[26:29]
	v_mfma_f32_16x16x32_bf16 v[14:17], v[200:203], v[236:239], v[14:17]
	v_mfma_f32_16x16x32_bf16 v[10:13], v[192:195], v[244:247], v[10:13]
	v_mfma_f32_16x16x32_bf16 v[2:5], v[200:203], v[244:247], v[2:5]
	s_barrier
	s_add_i32 s17, s17, 2
	s_add_u32 vcc_lo, vcc_lo, 0x100
	s_addc_u32 s16, s16, 0
	s_add_u32 s62, s62, 0x100
	s_addc_u32 s63, s63, 0
	s_cmp_gt_u32 s17, 61
	s_cbranch_scc1 .Lpeel_exit_0

; #define PG8_STAGE(bufoff, gbase, voff) do { _Pragma("unroll") for (int _i = 0; _i < 2; ++_i) \
;         __builtin_amdgcn_global_load_lds((const unsigned*)((const char*)(gbase) + (voff)[_i]), (PG8_LAS unsigned*)(lds + (bufoff) + ldsw + _i * 8192), 16, 0, 0); } while (0)
; #define PG8_LDA(dst, b, h) do { _Pragma("unroll") for (int m = 0; m < 4; ++m) _Pragma("unroll") for (int k = 0; k < 2; ++k) dst[m][k] = *(const PG8_LAS bf16x8*)(lds + PG8_SA(b, h) + aoff + m * 2048 + k * 1024); } while (0)
; #define PG8_LDB(dst, b, h) do { _Pragma("unroll") for (int n = 0; n < 2; ++n) _Pragma("unroll") for (int k = 0; k < 2; ++k) dst[n][k] = *(const PG8_LAS bf16x8*)(lds + PG8_SB(b, h) + boff + n * 2048 + k * 1024); } while (0)
; #define PG8_MMA(ai, bj, At, Bt) do { __builtin_amdgcn_s_setprio(1); _Pragma("unroll") for (int m = 0; m < 4; ++m) _Pragma("unroll") for (int n = 0; n < 2; ++n) _Pragma("unroll") for (int k = 0; k < 2; ++k) \
;         acc[ai][bj][m][n] = __builtin_amdgcn_mfma_f32_16x16x32_bf16(Bt[n][k], At[m][k], acc[ai][bj][m][n], 0, 0, 0); __builtin_amdgcn_s_setprio(0); } while (0)
; #define PG8_WAIT_V(n) asm volatile("s_waitcnt vmcnt(" #n ")" ::: "memory")
; #define PG8_WAIT_L(n) asm volatile("s_waitcnt lgkmcnt(" #n ")" ::: "memory")
; template <class Epi, class Sched, bool ALIGN_EPI = false, bool SP2 = false>
; __device__ __forceinline__ void gemm_phase(PG8_LAS unsigned char* lds, const Gemm g, const Sched& S, const Epi& E) {
;     ...
;             const bool last = (t == nt - 2);
;             const char* a1 = cA + (size_t)(t + 1) * kstep;
;             const char* a2 = last ? nA : cA + (size_t)(t + 2) * kstep; const char* b2 = last ? nB : cB + (size_t)(t + 2) * kstep;
;             const char* a3 = a2 + kstep; const char* b3 = b2 + kstep;
;             if (last && has_next) S.a_ready(nxt);
;             if constexpr (SP2) {
;             PG8_LDB(B0, 0, 0); PG8_LDB(B1, 0, 1); PG8_SCHED; PG8_LDA(At, 0, 0); PG8_STAGE(PG8_SA(1, 1), a1 + hstep, voffA);
;             PG8_WAIT_V(8); PG8_WAIT_L(0); PG8_BAR; PG8_MMA(0, 0, At, B0); PG8_MMA(0, 1, At, B1); PG8_BAR; PG8_SCHED;
;             PG8_LDA(At, 0, 1); PG8_STAGE(PG8_SB(0, 0), b2, voffB); PG8_STAGE(PG8_SB(0, 1), b2 + hstep, voffB); PG8_STAGE(PG8_SA(0, 0), a2, voffA);
;             PG8_WAIT_V(8); PG8_WAIT_L(0); PG8_BAR; PG8_MMA(1, 0, At, B0); PG8_MMA(1, 1, At, B1); PG8_BAR; PG8_SCHED;
.Lrb_skip_1:
	s_add_u32 s26, s48, 0xfff80080
	s_addc_u32 s27, s49, -1
	s_add_i32 s39, 0, 0x10000
	s_cmp_eq_u32 s17, 28
	s_cselect_b32 s29, s15, s27
	s_cselect_b32 s28, s30, s26
	s_cselect_b32 s27, s31, s16
	s_cselect_b32 s26, s34, s35
	s_add_i32 s41, 0, 0x14000
	v_add_u32_e32 v142, s39, v190
	v_add_u32_e32 v170, s41, v190
	ds_read_b128 v[130:133], v142
	ds_read_b128 v[134:137], v142 offset:1024
	ds_read_b128 v[138:141], v142 offset:2048
	ds_read_b128 v[142:145], v142 offset:3072
	ds_read_b128 v[146:149], v170
	ds_read_b128 v[150:153], v170 offset:1024
	ds_read_b128 v[178:181], v170 offset:2048
	ds_read_b128 v[182:185], v170 offset:3072
	v_lshl_add_u64 v[170:171], s[48:49], 0, v[176:177]
	s_add_i32 m0, s6, 0xc000
	ds_read_b128 v[186:189], v192
	ds_read_b128 v[194:197], v192 offset:1024
	ds_read_b128 v[198:201], v192 offset:2048
	ds_read_b128 v[202:205], v192 offset:3072
	ds_read_b128 v[206:209], v192 offset:4096
	ds_read_b128 v[220:223], v192 offset:5120
	ds_read_b128 v[224:227], v192 offset:6144
	ds_read_b128 v[228:231], v192 offset:7168
	global_load_lds_dwordx4 v[170:171], off
	v_lshl_add_u64 v[170:171], s[48:49], 0, v[174:175]
	s_add_i32 m0, s6, 0xe000
	s_nop 0
	global_load_lds_dwordx4 v[170:171], off
	s_waitcnt vmcnt(8)
	s_waitcnt lgkmcnt(0)
	s_barrier
	v_mfma_f32_16x16x32_bf16 v[126:129], v[130:133], v[186:189], 0
	v_mfma_f32_16x16x32_bf16 v[122:125], v[138:141], v[186:189], 0
	v_mfma_f32_16x16x32_bf16 v[110:113], v[130:133], v[198:201], 0
	v_mfma_f32_16x16x32_bf16 v[106:109], v[138:141], v[198:201], 0
	v_mfma_f32_16x16x32_bf16 v[94:97], v[130:133], v[206:209], 0
	v_mfma_f32_16x16x32_bf16 v[90:93], v[138:141], v[206:209], 0
	v_mfma_f32_16x16x32_bf16 v[78:81], v[130:133], v[224:227], 0
	v_mfma_f32_16x16x32_bf16 v[74:77], v[138:141], v[224:227], 0
	v_mfma_f32_16x16x32_bf16 v[126:129], v[134:137], v[194:197], v[126:129]
	v_mfma_f32_16x16x32_bf16 v[122:125], v[142:145], v[194:197], v[122:125]
	v_mfma_f32_16x16x32_bf16 v[110:113], v[134:137], v[202:205], v[110:113]
	v_mfma_f32_16x16x32_bf16 v[106:109], v[142:145], v[202:205], v[106:109]
	v_mfma_f32_16x16x32_bf16 v[94:97], v[134:137], v[220:223], v[94:97]
	v_mfma_f32_16x16x32_bf16 v[90:93], v[142:145], v[220:223], v[90:93]
	v_mfma_f32_16x16x32_bf16 v[78:81], v[134:137], v[228:231], v[78:81]
	v_mfma_f32_16x16x32_bf16 v[74:77], v[142:145], v[228:231], v[74:77]
	v_mfma_f32_16x16x32_bf16 v[118:121], v[146:149], v[186:189], 0
	v_mfma_f32_16x16x32_bf16 v[114:117], v[178:181], v[186:189], 0
	v_mfma_f32_16x16x32_bf16 v[102:105], v[146:149], v[198:201], 0
	v_mfma_f32_16x16x32_bf16 v[98:101], v[178:181], v[198:201], 0
	v_mfma_f32_16x16x32_bf16 v[86:89], v[146:149], v[206:209], 0
	v_mfma_f32_16x16x32_bf16 v[82:85], v[178:181], v[206:209], 0
	v_mfma_f32_16x16x32_bf16 v[70:73], v[146:149], v[224:227], 0
	v_mfma_f32_16x16x32_bf16 v[66:69], v[178:181], v[224:227], 0
	v_mfma_f32_16x16x32_bf16 v[118:121], v[150:153], v[194:197], v[118:121]
	v_mfma_f32_16x16x32_bf16 v[114:117], v[182:185], v[194:197], v[114:117]
	v_mfma_f32_16x16x32_bf16 v[102:105], v[150:153], v[202:205], v[102:105]
	v_mfma_f32_16x16x32_bf16 v[98:101], v[182:185], v[202:205], v[98:101]
	v_mfma_f32_16x16x32_bf16 v[86:89], v[150:153], v[220:223], v[86:89]
	v_mfma_f32_16x16x32_bf16 v[82:85], v[182:185], v[220:223], v[82:85]
	v_mfma_f32_16x16x32_bf16 v[70:73], v[150:153], v[228:231], v[70:73]
	v_mfma_f32_16x16x32_bf16 v[66:69], v[182:185], v[228:231], v[66:69]
	s_barrier
	s_add_i32 s39, s39, s5
	v_lshl_add_u64 v[170:171], s[26:27], 0, v[158:159]
	s_mov_b32 m0, s39
	ds_read_b128 v[186:189], v192 offset:16384
	ds_read_b128 v[194:197], v192 offset:17408
	ds_read_b128 v[198:201], v192 offset:18432
	ds_read_b128 v[202:205], v192 offset:19456
	ds_read_b128 v[206:209], v192 offset:20480
	ds_read_b128 v[220:223], v192 offset:21504
	ds_read_b128 v[224:227], v192 offset:22528
	ds_read_b128 v[228:231], v192 offset:23552
	global_load_lds_dwordx4 v[170:171], off
	s_add_i32 m0, s39, 0x2000
	s_add_u32 s50, s26, 0x80000
	v_lshl_add_u64 v[210:211], s[26:27], 0, v[154:155]
	s_addc_u32 s51, s27, 0
	s_add_i32 s39, s41, s5
	global_load_lds_dwordx4 v[210:211], off
	v_lshl_add_u64 v[232:233], s[50:51], 0, v[158:159]
	s_mov_b32 m0, s39
	v_lshl_add_u64 v[234:235], s[28:29], 0, v[156:157]
	global_load_lds_dwordx4 v[232:233], off
	v_lshl_add_u64 v[232:233], s[50:51], 0, v[154:155]
	s_add_i32 m0, s39, 0x2000
	s_nop 0
	global_load_lds_dwordx4 v[232:233], off
	v_lshl_add_u64 v[232:233], s[28:29], 0, v[172:173]
	s_mov_b32 m0, s6
	s_nop 0
	global_load_lds_dwordx4 v[232:233], off
	s_mov_b32 m0, s7
	s_nop 0
	global_load_lds_dwordx4 v[234:235], off
	s_waitcnt vmcnt(8)
	s_waitcnt lgkmcnt(0)
	s_barrier
; #define PG8_STAGE(bufoff, gbase, voff) do { _Pragma("unroll") for (int _i = 0; _i < 2; ++_i) \
;         __builtin_amdgcn_global_load_lds((const unsigned*)((const char*)(gbase) + (voff)[_i]), (PG8_LAS unsigned*)(lds + (bufoff) + ldsw + _i * 8192), 16, 0, 0); } while (0)
; #define PG8_LDA(dst, b, h) do { _Pragma("unroll") for (int m = 0; m < 4; ++m) _Pragma("unroll") for (int k = 0; k < 2; ++k) dst[m][k] = *(const PG8_LAS bf16x8*)(lds + PG8_SA(b, h) + aoff + m * 2048 + k * 1024); } while (0)
; #define PG8_LDB(dst, b, h) do { _Pragma("unroll") for (int n = 0; n < 2; ++n) _Pragma("unroll") for (int k = 0; k < 2; ++k) dst[n][k] = *(const PG8_LAS bf16x8*)(lds + PG8_SB(b, h) + boff + n * 2048 + k * 1024); } while (0)
; #define PG8_MMA(ai, bj, At, Bt) do { __builtin_amdgcn_s_setprio(1); _Pragma("unroll") for (int m = 0; m < 4; ++m) _Pragma("unroll") for (int n = 0; n < 2; ++n) _Pragma("unroll") for (int k = 0; k < 2; ++k) \
;         acc[ai][bj][m][n] = __builtin_amdgcn_mfma_f32_16x16x32_bf16(Bt[n][k], At[m][k], acc[ai][bj][m][n], 0, 0, 0); __builtin_amdgcn_s_setprio(0); } while (0)
; #define PG8_WAIT_V(n) asm volatile("s_waitcnt vmcnt(" #n ")" ::: "memory")
; #define PG8_WAIT_L(n) asm volatile("s_waitcnt lgkmcnt(" #n ")" ::: "memory")
; #define PG8_BAR __builtin_amdgcn_s_barrier()
; #define PG8_SCHED __builtin_amdgcn_sched_barrier(0)
; template <class Epi, class Sched, bool ALIGN_EPI = false, bool SP2 = false>
; __device__ __forceinline__ void gemm_phase(PG8_LAS unsigned char* lds, const Gemm g, const Sched& S, const Epi& E) {
;     ...
;             PG8_WAIT_V(8); PG8_WAIT_L(0); PG8_BAR; PG8_MMA(1, 0, At, B0); PG8_MMA(1, 1, At, B1); PG8_BAR; PG8_SCHED;
;             PG8_LDB(B0, 1, 0); PG8_LDB(B1, 1, 1); PG8_SCHED; PG8_LDA(At, 1, 0); PG8_STAGE(PG8_SA(0, 1), a2 + hstep, voffA);
;             PG8_WAIT_V(8); PG8_WAIT_L(0); PG8_BAR; PG8_MMA(0, 0, At, B0); PG8_MMA(0, 1, At, B1); PG8_BAR; PG8_SCHED;
	v_mfma_f32_16x16x32_bf16 v[62:65], v[130:133], v[186:189], 0
	v_mfma_f32_16x16x32_bf16 v[58:61], v[138:141], v[186:189], 0
	v_mfma_f32_16x16x32_bf16 v[46:49], v[130:133], v[198:201], 0
	v_mfma_f32_16x16x32_bf16 v[42:45], v[138:141], v[198:201], 0
	v_mfma_f32_16x16x32_bf16 v[30:33], v[130:133], v[206:209], 0
	v_mfma_f32_16x16x32_bf16 v[26:29], v[138:141], v[206:209], 0
	v_mfma_f32_16x16x32_bf16 v[14:17], v[130:133], v[224:227], 0
	v_mfma_f32_16x16x32_bf16 v[10:13], v[138:141], v[224:227], 0
	v_mfma_f32_16x16x32_bf16 v[62:65], v[134:137], v[194:197], v[62:65]
	v_mfma_f32_16x16x32_bf16 v[58:61], v[142:145], v[194:197], v[58:61]
	v_mfma_f32_16x16x32_bf16 v[46:49], v[134:137], v[202:205], v[46:49]
	v_mfma_f32_16x16x32_bf16 v[42:45], v[142:145], v[202:205], v[42:45]
	v_mfma_f32_16x16x32_bf16 v[30:33], v[134:137], v[220:223], v[30:33]
	v_mfma_f32_16x16x32_bf16 v[26:29], v[142:145], v[220:223], v[26:29]
	v_mfma_f32_16x16x32_bf16 v[14:17], v[134:137], v[228:231], v[14:17]
	v_mfma_f32_16x16x32_bf16 v[10:13], v[142:145], v[228:231], v[10:13]
	v_mfma_f32_16x16x32_bf16 v[54:57], v[146:149], v[186:189], 0
	v_mfma_f32_16x16x32_bf16 v[50:53], v[178:181], v[186:189], 0
	v_mfma_f32_16x16x32_bf16 v[38:41], v[146:149], v[198:201], 0
	v_mfma_f32_16x16x32_bf16 v[34:37], v[178:181], v[198:201], 0
	v_mfma_f32_16x16x32_bf16 v[22:25], v[146:149], v[206:209], 0
	v_mfma_f32_16x16x32_bf16 v[18:21], v[178:181], v[206:209], 0
	v_mfma_f32_16x16x32_bf16 v[6:9], v[146:149], v[224:227], 0
	v_mfma_f32_16x16x32_bf16 v[2:5], v[178:181], v[224:227], 0
	v_mfma_f32_16x16x32_bf16 v[54:57], v[150:153], v[194:197], v[54:57]
	v_mfma_f32_16x16x32_bf16 v[50:53], v[182:185], v[194:197], v[50:53]
	v_mfma_f32_16x16x32_bf16 v[38:41], v[150:153], v[202:205], v[38:41]
	v_mfma_f32_16x16x32_bf16 v[34:37], v[182:185], v[202:205], v[34:37]
	v_mfma_f32_16x16x32_bf16 v[22:25], v[150:153], v[220:223], v[22:25]
	v_mfma_f32_16x16x32_bf16 v[18:21], v[182:185], v[220:223], v[18:21]
	v_mfma_f32_16x16x32_bf16 v[6:9], v[150:153], v[228:231], v[6:9]
	v_mfma_f32_16x16x32_bf16 v[2:5], v[182:185], v[228:231], v[2:5]
	s_barrier
	s_add_i32 s39, 0, 0x18000
	s_add_i32 s41, 0, 0x1c000
	v_add_u32_e32 v142, s39, v190
	v_add_u32_e32 v182, s41, v190
	ds_read_b128 v[130:133], v142
	ds_read_b128 v[134:137], v142 offset:1024
	ds_read_b128 v[138:141], v142 offset:2048
	ds_read_b128 v[142:145], v142 offset:3072
	ds_read_b128 v[146:149], v182
	ds_read_b128 v[150:153], v182 offset:1024
	ds_read_b128 v[178:181], v182 offset:2048
	ds_read_b128 v[182:185], v182 offset:3072
	s_add_u32 s28, s28, 0x80000
	s_addc_u32 s29, s29, 0
	s_mov_b32 m0, s8
	v_lshl_add_u64 v[236:237], s[28:29], 0, v[172:173]
	ds_read_b128 v[186:189], v192 offset:32768
	ds_read_b128 v[194:197], v192 offset:33792
	ds_read_b128 v[198:201], v192 offset:34816
	ds_read_b128 v[202:205], v192 offset:35840
	ds_read_b128 v[206:209], v192 offset:36864
	ds_read_b128 v[220:223], v192 offset:37888
	ds_read_b128 v[224:227], v192 offset:38912
	ds_read_b128 v[228:231], v192 offset:39936
	global_load_lds_dwordx4 v[236:237], off
	v_lshl_add_u64 v[236:237], s[28:29], 0, v[156:157]
	s_mov_b32 m0, s9
	s_nop 0
	global_load_lds_dwordx4 v[236:237], off
	s_waitcnt vmcnt(8)
	s_waitcnt lgkmcnt(0)
	s_barrier
	v_mfma_f32_16x16x32_bf16 v[126:129], v[130:133], v[186:189], v[126:129]
	v_mfma_f32_16x16x32_bf16 v[122:125], v[138:141], v[186:189], v[122:125]
	v_mfma_f32_16x16x32_bf16 v[110:113], v[130:133], v[198:201], v[110:113]
	v_mfma_f32_16x16x32_bf16 v[106:109], v[138:141], v[198:201], v[106:109]
	v_mfma_f32_16x16x32_bf16 v[94:97], v[130:133], v[206:209], v[94:97]
	v_mfma_f32_16x16x32_bf16 v[90:93], v[138:141], v[206:209], v[90:93]
	v_mfma_f32_16x16x32_bf16 v[78:81], v[130:133], v[224:227], v[78:81]
	v_mfma_f32_16x16x32_bf16 v[74:77], v[138:141], v[224:227], v[74:77]
	v_mfma_f32_16x16x32_bf16 v[126:129], v[134:137], v[194:197], v[126:129]
	v_mfma_f32_16x16x32_bf16 v[122:125], v[142:145], v[194:197], v[122:125]
	v_mfma_f32_16x16x32_bf16 v[110:113], v[134:137], v[202:205], v[110:113]
	v_mfma_f32_16x16x32_bf16 v[106:109], v[142:145], v[202:205], v[106:109]
	v_mfma_f32_16x16x32_bf16 v[94:97], v[134:137], v[220:223], v[94:97]
	v_mfma_f32_16x16x32_bf16 v[90:93], v[142:145], v[220:223], v[90:93]
	v_mfma_f32_16x16x32_bf16 v[78:81], v[134:137], v[228:231], v[78:81]
	v_mfma_f32_16x16x32_bf16 v[74:77], v[142:145], v[228:231], v[74:77]
	v_mfma_f32_16x16x32_bf16 v[118:121], v[146:149], v[186:189], v[118:121]
	v_mfma_f32_16x16x32_bf16 v[114:117], v[178:181], v[186:189], v[114:117]
	v_mfma_f32_16x16x32_bf16 v[102:105], v[146:149], v[198:201], v[102:105]
	v_mfma_f32_16x16x32_bf16 v[98:101], v[178:181], v[198:201], v[98:101]
	v_mfma_f32_16x16x32_bf16 v[86:89], v[146:149], v[206:209], v[86:89]
	v_mfma_f32_16x16x32_bf16 v[82:85], v[178:181], v[206:209], v[82:85]
	v_mfma_f32_16x16x32_bf16 v[70:73], v[146:149], v[224:227], v[70:73]
	v_mfma_f32_16x16x32_bf16 v[66:69], v[178:181], v[224:227], v[66:69]
	v_mfma_f32_16x16x32_bf16 v[118:121], v[150:153], v[194:197], v[118:121]
	v_mfma_f32_16x16x32_bf16 v[114:117], v[182:185], v[194:197], v[114:117]
	v_mfma_f32_16x16x32_bf16 v[102:105], v[150:153], v[202:205], v[102:105]
	v_mfma_f32_16x16x32_bf16 v[98:101], v[182:185], v[202:205], v[98:101]
	v_mfma_f32_16x16x32_bf16 v[86:89], v[150:153], v[220:223], v[86:89]
	v_mfma_f32_16x16x32_bf16 v[82:85], v[182:185], v[220:223], v[82:85]
	v_mfma_f32_16x16x32_bf16 v[70:73], v[150:153], v[228:231], v[70:73]
	v_mfma_f32_16x16x32_bf16 v[66:69], v[182:185], v[228:231], v[66:69]
	s_barrier
; #define PG8_STAGE(bufoff, gbase, voff) do { _Pragma("unroll") for (int _i = 0; _i < 2; ++_i) \
;         __builtin_amdgcn_global_load_lds((const unsigned*)((const char*)(gbase) + (voff)[_i]), (PG8_LAS unsigned*)(lds + (bufoff) + ldsw + _i * 8192), 16, 0, 0); } while (0)
; #define PG8_LDA(dst, b, h) do { _Pragma("unroll") for (int m = 0; m < 4; ++m) _Pragma("unroll") for (int k = 0; k < 2; ++k) dst[m][k] = *(const PG8_LAS bf16x8*)(lds + PG8_SA(b, h) + aoff + m * 2048 + k * 1024); } while (0)
; #define PG8_MMA(ai, bj, At, Bt) do { __builtin_amdgcn_s_setprio(1); _Pragma("unroll") for (int m = 0; m < 4; ++m) _Pragma("unroll") for (int n = 0; n < 2; ++n) _Pragma("unroll") for (int k = 0; k < 2; ++k) \
;         acc[ai][bj][m][n] = __builtin_amdgcn_mfma_f32_16x16x32_bf16(Bt[n][k], At[m][k], acc[ai][bj][m][n], 0, 0, 0); __builtin_amdgcn_s_setprio(0); } while (0)
; #define PG8_WAIT_V(n) asm volatile("s_waitcnt vmcnt(" #n ")" ::: "memory")
; #define PG8_WAIT_L(n) asm volatile("s_waitcnt lgkmcnt(" #n ")" ::: "memory")
; #define PG8_BAR __builtin_amdgcn_s_barrier()
; #define PG8_SCHED __builtin_amdgcn_sched_barrier(0)
; template <class Epi, class Sched, bool ALIGN_EPI = false, bool SP2 = false>
; __device__ __forceinline__ void gemm_phase(PG8_LAS unsigned char* lds, const Gemm g, const Sched& S, const Epi& E) {
;     ...
;             PG8_LDA(At, 1, 1); PG8_STAGE(PG8_SB(1, 0), b3, voffB); PG8_STAGE(PG8_SB(1, 1), b3 + hstep, voffB); PG8_STAGE(PG8_SA(1, 0), a3, voffA);
;             PG8_WAIT_V(8); PG8_WAIT_L(0); PG8_BAR; PG8_MMA(1, 0, At, B0); PG8_MMA(1, 1, At, B1); PG8_BAR; PG8_SCHED;
	s_add_i32 s28, s39, s5
	v_lshl_add_u64 v[170:171], v[170:171], 0, s[96:97]
	s_mov_b32 m0, s28
	ds_read_b128 v[186:189], v192 offset:49152
	ds_read_b128 v[194:197], v192 offset:50176
	ds_read_b128 v[198:201], v192 offset:51200
	ds_read_b128 v[202:205], v192 offset:52224
	ds_read_b128 v[206:209], v192 offset:53248
	ds_read_b128 v[220:223], v192 offset:54272
	ds_read_b128 v[224:227], v192 offset:55296
	ds_read_b128 v[228:231], v192 offset:56320
	global_load_lds_dwordx4 v[170:171], off
	s_add_i32 m0, s28, 0x2000
	s_add_u32 s26, s26, 0x80080
	v_lshl_add_u64 v[170:171], v[210:211], 0, s[96:97]
	s_addc_u32 s27, s27, 0
	s_add_i32 s28, s41, s5
	global_load_lds_dwordx4 v[170:171], off
	v_lshl_add_u64 v[170:171], s[26:27], 0, v[158:159]
	s_mov_b32 m0, s28
	s_nop 0
	global_load_lds_dwordx4 v[170:171], off
	v_lshl_add_u64 v[170:171], s[26:27], 0, v[154:155]
	s_add_i32 m0, s28, 0x2000
	s_nop 0
	global_load_lds_dwordx4 v[170:171], off
	v_lshl_add_u64 v[170:171], v[232:233], 0, s[96:97]
	s_mov_b32 m0, s10
	s_nop 0
	global_load_lds_dwordx4 v[170:171], off
	v_lshl_add_u64 v[170:171], v[234:235], 0, s[96:97]
	s_mov_b32 m0, s11
	s_nop 0
	global_load_lds_dwordx4 v[170:171], off
	s_waitcnt vmcnt(8)
	s_waitcnt lgkmcnt(0)
	s_barrier
	v_mfma_f32_16x16x32_bf16 v[62:65], v[130:133], v[186:189], v[62:65]
	v_mfma_f32_16x16x32_bf16 v[58:61], v[138:141], v[186:189], v[58:61]
	v_mfma_f32_16x16x32_bf16 v[46:49], v[130:133], v[198:201], v[46:49]
	v_mfma_f32_16x16x32_bf16 v[42:45], v[138:141], v[198:201], v[42:45]
	v_mfma_f32_16x16x32_bf16 v[30:33], v[130:133], v[206:209], v[30:33]
	v_mfma_f32_16x16x32_bf16 v[26:29], v[138:141], v[206:209], v[26:29]
	v_mfma_f32_16x16x32_bf16 v[14:17], v[130:133], v[224:227], v[14:17]
	v_mfma_f32_16x16x32_bf16 v[10:13], v[138:141], v[224:227], v[10:13]
	v_mfma_f32_16x16x32_bf16 v[62:65], v[134:137], v[194:197], v[62:65]
	v_mfma_f32_16x16x32_bf16 v[58:61], v[142:145], v[194:197], v[58:61]
	v_mfma_f32_16x16x32_bf16 v[46:49], v[134:137], v[202:205], v[46:49]
	v_mfma_f32_16x16x32_bf16 v[42:45], v[142:145], v[202:205], v[42:45]
	v_mfma_f32_16x16x32_bf16 v[30:33], v[134:137], v[220:223], v[30:33]
	v_mfma_f32_16x16x32_bf16 v[26:29], v[142:145], v[220:223], v[26:29]
	v_mfma_f32_16x16x32_bf16 v[14:17], v[134:137], v[228:231], v[14:17]
	v_mfma_f32_16x16x32_bf16 v[10:13], v[142:145], v[228:231], v[10:13]
	v_mfma_f32_16x16x32_bf16 v[54:57], v[146:149], v[186:189], v[54:57]
	v_mfma_f32_16x16x32_bf16 v[50:53], v[178:181], v[186:189], v[50:53]
	v_mfma_f32_16x16x32_bf16 v[38:41], v[146:149], v[198:201], v[38:41]
	v_mfma_f32_16x16x32_bf16 v[34:37], v[178:181], v[198:201], v[34:37]
	v_mfma_f32_16x16x32_bf16 v[22:25], v[146:149], v[206:209], v[22:25]
	v_mfma_f32_16x16x32_bf16 v[18:21], v[178:181], v[206:209], v[18:21]
	v_mfma_f32_16x16x32_bf16 v[6:9], v[146:149], v[224:227], v[6:9]
	v_mfma_f32_16x16x32_bf16 v[2:5], v[178:181], v[224:227], v[2:5]
	v_mfma_f32_16x16x32_bf16 v[54:57], v[150:153], v[194:197], v[54:57]
	v_mfma_f32_16x16x32_bf16 v[50:53], v[182:185], v[194:197], v[50:53]
	v_mfma_f32_16x16x32_bf16 v[38:41], v[150:153], v[202:205], v[38:41]
	v_mfma_f32_16x16x32_bf16 v[34:37], v[182:185], v[202:205], v[34:37]
	v_mfma_f32_16x16x32_bf16 v[22:25], v[150:153], v[220:223], v[22:25]
	v_mfma_f32_16x16x32_bf16 v[18:21], v[182:185], v[220:223], v[18:21]
	v_mfma_f32_16x16x32_bf16 v[6:9], v[150:153], v[228:231], v[6:9]
	v_mfma_f32_16x16x32_bf16 v[2:5], v[182:185], v[228:231], v[2:5]
	s_barrier
	s_add_i32 s17, s17, 2
	s_add_u32 s35, s35, 0x100
	s_addc_u32 s16, s16, 0
	s_add_u32 s48, s48, 0x100
	s_addc_u32 s49, s49, 0
	s_cmp_gt_u32 s17, 29
	s_cbranch_scc1 .Lpeel_exit_1

; #define PG8_STAGE(bufoff, gbase, voff) do { _Pragma("unroll") for (int _i = 0; _i < 2; ++_i) \
;         __builtin_amdgcn_global_load_lds((const unsigned*)((const char*)(gbase) + (voff)[_i]), (PG8_LAS unsigned*)(lds + (bufoff) + ldsw + _i * 8192), 16, 0, 0); } while (0)
; #define PG8_LDA(dst, b, h) do { _Pragma("unroll") for (int m = 0; m < 4; ++m) _Pragma("unroll") for (int k = 0; k < 2; ++k) dst[m][k] = *(const PG8_LAS bf16x8*)(lds + PG8_SA(b, h) + aoff + m * 2048 + k * 1024); } while (0)
; #define PG8_LDB(dst, b, h) do { _Pragma("unroll") for (int n = 0; n < 2; ++n) _Pragma("unroll") for (int k = 0; k < 2; ++k) dst[n][k] = *(const PG8_LAS bf16x8*)(lds + PG8_SB(b, h) + boff + n * 2048 + k * 1024); } while (0)
; #define PG8_MMA(ai, bj, At, Bt) do { __builtin_amdgcn_s_setprio(1); _Pragma("unroll") for (int m = 0; m < 4; ++m) _Pragma("unroll") for (int n = 0; n < 2; ++n) _Pragma("unroll") for (int k = 0; k < 2; ++k) \
;         acc[ai][bj][m][n] = __builtin_amdgcn_mfma_f32_16x16x32_bf16(Bt[n][k], At[m][k], acc[ai][bj][m][n], 0, 0, 0); __builtin_amdgcn_s_setprio(0); } while (0)
; #define PG8_WAIT_V(n) asm volatile("s_waitcnt vmcnt(" #n ")" ::: "memory")
; #define PG8_BAR __builtin_amdgcn_s_barrier()
; template <class Epi, class Sched, bool ALIGN_EPI = false, bool SP2 = false>
; __device__ __forceinline__ void gemm_phase(PG8_LAS unsigned char* lds, const Gemm g, const Sched& S, const Epi& E) {
;     ...
;         for (int t = 0; t < nt; t += 2) {
;             const bool last = (t == nt - 2);
;             const char* a1 = cA + (size_t)(t + 1) * kstep;
;             const char* a2 = last ? nA : cA + (size_t)(t + 2) * kstep; const char* b2 = last ? nB : cB + (size_t)(t + 2) * kstep;
;             const char* a3 = a2 + kstep; const char* b3 = b2 + kstep;
;             if (last && has_next) S.a_ready(nxt);
;             if constexpr (SP2) {
;             PG8_LDB(B0, 0, 0); PG8_LDB(B1, 0, 1); PG8_SCHED; PG8_LDA(At, 0, 0); PG8_STAGE(PG8_SA(1, 1), a1 + hstep, voffA);
;             PG8_WAIT_V(8); PG8_WAIT_L(0); PG8_BAR; PG8_MMA(0, 0, At, B0); PG8_MMA(0, 1, At, B1); PG8_BAR; PG8_SCHED;
;             PG8_LDA(At, 0, 1); PG8_STAGE(PG8_SB(0, 0), b2, voffB); PG8_STAGE(PG8_SB(0, 1), b2 + hstep, voffB); PG8_STAGE(PG8_SA(0, 0), a2, voffA);
;             PG8_WAIT_V(8); PG8_WAIT_L(0); PG8_BAR; PG8_MMA(1, 0, At, B0); PG8_MMA(1, 1, At, B1); PG8_BAR; PG8_SCHED;
.Lrb_skip_2:
	s_add_i32 s21, s17, 2
	s_add_u32 s23, s24, 0xfff00080
	s_addc_u32 s26, s25, -1
	s_add_i32 s30, 0, 0x10000
	s_cmp_eq_u32 s14, s17
	s_cselect_b32 s29, s55, s26
	s_cselect_b32 s28, s54, s23
	s_cselect_b32 s27, s57, s16
	s_cselect_b32 s26, s56, s15
	s_add_i32 s17, 0, 0x14000
	v_add_u32_e32 v142, s30, v190
	v_add_u32_e32 v170, s17, v190
	ds_read_b128 v[130:133], v142
	ds_read_b128 v[134:137], v142 offset:1024
	ds_read_b128 v[138:141], v142 offset:2048
	ds_read_b128 v[142:145], v142 offset:3072
	ds_read_b128 v[146:149], v170
	ds_read_b128 v[150:153], v170 offset:1024
	ds_read_b128 v[178:181], v170 offset:2048
	ds_read_b128 v[182:185], v170 offset:3072
	v_lshl_add_u64 v[170:171], s[24:25], 0, v[176:177]
	s_add_i32 m0, s35, 0xc000
	ds_read_b128 v[186:189], v192
	ds_read_b128 v[194:197], v192 offset:1024
	ds_read_b128 v[198:201], v192 offset:2048
	ds_read_b128 v[202:205], v192 offset:3072
	ds_read_b128 v[206:209], v192 offset:4096
	ds_read_b128 v[220:223], v192 offset:5120
	ds_read_b128 v[224:227], v192 offset:6144
	ds_read_b128 v[228:231], v192 offset:7168
	global_load_lds_dwordx4 v[170:171], off
	v_lshl_add_u64 v[170:171], s[24:25], 0, v[174:175]
	s_add_i32 m0, s35, 0xe000
	s_nop 0
	global_load_lds_dwordx4 v[170:171], off
	s_waitcnt vmcnt(8)
	s_waitcnt lgkmcnt(0)
	s_barrier
	v_mfma_f32_16x16x32_bf16 v[126:129], v[130:133], v[186:189], 0
	v_mfma_f32_16x16x32_bf16 v[122:125], v[138:141], v[186:189], 0
	v_mfma_f32_16x16x32_bf16 v[118:121], v[130:133], v[198:201], 0
	v_mfma_f32_16x16x32_bf16 v[114:117], v[138:141], v[198:201], 0
	v_mfma_f32_16x16x32_bf16 v[102:105], v[130:133], v[206:209], 0
	v_mfma_f32_16x16x32_bf16 v[94:97], v[138:141], v[206:209], 0
	v_mfma_f32_16x16x32_bf16 v[86:89], v[130:133], v[224:227], 0
	v_mfma_f32_16x16x32_bf16 v[78:81], v[138:141], v[224:227], 0
	v_mfma_f32_16x16x32_bf16 v[126:129], v[134:137], v[194:197], v[126:129]
	v_mfma_f32_16x16x32_bf16 v[122:125], v[142:145], v[194:197], v[122:125]
	v_mfma_f32_16x16x32_bf16 v[118:121], v[134:137], v[202:205], v[118:121]
	v_mfma_f32_16x16x32_bf16 v[114:117], v[142:145], v[202:205], v[114:117]
	v_mfma_f32_16x16x32_bf16 v[102:105], v[134:137], v[220:223], v[102:105]
	v_mfma_f32_16x16x32_bf16 v[94:97], v[142:145], v[220:223], v[94:97]
	v_mfma_f32_16x16x32_bf16 v[86:89], v[134:137], v[228:231], v[86:89]
	v_mfma_f32_16x16x32_bf16 v[78:81], v[142:145], v[228:231], v[78:81]
	v_mfma_f32_16x16x32_bf16 v[110:113], v[146:149], v[186:189], 0
	v_mfma_f32_16x16x32_bf16 v[106:109], v[178:181], v[186:189], 0
	v_mfma_f32_16x16x32_bf16 v[98:101], v[146:149], v[198:201], 0
	v_mfma_f32_16x16x32_bf16 v[90:93], v[178:181], v[198:201], 0
	v_mfma_f32_16x16x32_bf16 v[82:85], v[146:149], v[206:209], 0
	v_mfma_f32_16x16x32_bf16 v[74:77], v[178:181], v[206:209], 0
	v_mfma_f32_16x16x32_bf16 v[70:73], v[146:149], v[224:227], 0
	v_mfma_f32_16x16x32_bf16 v[66:69], v[178:181], v[224:227], 0
	v_mfma_f32_16x16x32_bf16 v[110:113], v[150:153], v[194:197], v[110:113]
	v_mfma_f32_16x16x32_bf16 v[106:109], v[182:185], v[194:197], v[106:109]
	v_mfma_f32_16x16x32_bf16 v[98:101], v[150:153], v[202:205], v[98:101]
	v_mfma_f32_16x16x32_bf16 v[90:93], v[182:185], v[202:205], v[90:93]
	v_mfma_f32_16x16x32_bf16 v[82:85], v[150:153], v[220:223], v[82:85]
	v_mfma_f32_16x16x32_bf16 v[74:77], v[182:185], v[220:223], v[74:77]
	v_mfma_f32_16x16x32_bf16 v[70:73], v[150:153], v[228:231], v[70:73]
	v_mfma_f32_16x16x32_bf16 v[66:69], v[182:185], v[228:231], v[66:69]
	s_barrier
	s_add_i32 s23, s30, s34
	v_lshl_add_u64 v[170:171], s[26:27], 0, v[158:159]
	s_mov_b32 m0, s23
	ds_read_b128 v[186:189], v192 offset:16384
	ds_read_b128 v[194:197], v192 offset:17408
	ds_read_b128 v[198:201], v192 offset:18432
	ds_read_b128 v[202:205], v192 offset:19456
	ds_read_b128 v[206:209], v192 offset:20480
	ds_read_b128 v[220:223], v192 offset:21504
	ds_read_b128 v[224:227], v192 offset:22528
	ds_read_b128 v[228:231], v192 offset:23552
	global_load_lds_dwordx4 v[170:171], off
	s_add_i32 m0, s23, 0x2000
	s_add_u32 s58, s26, 0x100000
	v_lshl_add_u64 v[210:211], s[26:27], 0, v[172:173]
	s_addc_u32 s59, s27, 0
	s_add_i32 s17, s17, s34
	global_load_lds_dwordx4 v[210:211], off
	v_lshl_add_u64 v[232:233], s[58:59], 0, v[158:159]
	s_mov_b32 m0, s17
	v_lshl_add_u64 v[234:235], s[28:29], 0, v[156:157]
	global_load_lds_dwordx4 v[232:233], off
	v_lshl_add_u64 v[232:233], s[58:59], 0, v[172:173]
	s_add_i32 m0, s17, 0x2000
	s_nop 0
	global_load_lds_dwordx4 v[232:233], off
	v_lshl_add_u64 v[232:233], s[28:29], 0, v[154:155]
	s_mov_b32 m0, s35
	s_nop 0
	global_load_lds_dwordx4 v[232:233], off
	s_mov_b32 m0, s4
	s_nop 0
	global_load_lds_dwordx4 v[234:235], off
	s_waitcnt vmcnt(8)
	s_waitcnt lgkmcnt(0)
	s_barrier
; #define PG8_STAGE(bufoff, gbase, voff) do { _Pragma("unroll") for (int _i = 0; _i < 2; ++_i) \
;         __builtin_amdgcn_global_load_lds((const unsigned*)((const char*)(gbase) + (voff)[_i]), (PG8_LAS unsigned*)(lds + (bufoff) + ldsw + _i * 8192), 16, 0, 0); } while (0)
; #define PG8_LDA(dst, b, h) do { _Pragma("unroll") for (int m = 0; m < 4; ++m) _Pragma("unroll") for (int k = 0; k < 2; ++k) dst[m][k] = *(const PG8_LAS bf16x8*)(lds + PG8_SA(b, h) + aoff + m * 2048 + k * 1024); } while (0)
; #define PG8_LDB(dst, b, h) do { _Pragma("unroll") for (int n = 0; n < 2; ++n) _Pragma("unroll") for (int k = 0; k < 2; ++k) dst[n][k] = *(const PG8_LAS bf16x8*)(lds + PG8_SB(b, h) + boff + n * 2048 + k * 1024); } while (0)
; #define PG8_MMA(ai, bj, At, Bt) do { __builtin_amdgcn_s_setprio(1); _Pragma("unroll") for (int m = 0; m < 4; ++m) _Pragma("unroll") for (int n = 0; n < 2; ++n) _Pragma("unroll") for (int k = 0; k < 2; ++k) \
;         acc[ai][bj][m][n] = __builtin_amdgcn_mfma_f32_16x16x32_bf16(Bt[n][k], At[m][k], acc[ai][bj][m][n], 0, 0, 0); __builtin_amdgcn_s_setprio(0); } while (0)
; #define PG8_WAIT_V(n) asm volatile("s_waitcnt vmcnt(" #n ")" ::: "memory")
; #define PG8_WAIT_L(n) asm volatile("s_waitcnt lgkmcnt(" #n ")" ::: "memory")
; #define PG8_BAR __builtin_amdgcn_s_barrier()
; #define PG8_SCHED __builtin_amdgcn_sched_barrier(0)
; template <class Epi, class Sched, bool ALIGN_EPI = false, bool SP2 = false>
; __device__ __forceinline__ void gemm_phase(PG8_LAS unsigned char* lds, const Gemm g, const Sched& S, const Epi& E) {
;     ...
;             PG8_WAIT_V(8); PG8_WAIT_L(0); PG8_BAR; PG8_MMA(1, 0, At, B0); PG8_MMA(1, 1, At, B1); PG8_BAR; PG8_SCHED;
;             PG8_LDB(B0, 1, 0); PG8_LDB(B1, 1, 1); PG8_SCHED; PG8_LDA(At, 1, 0); PG8_STAGE(PG8_SA(0, 1), a2 + hstep, voffA);
;             PG8_WAIT_V(8); PG8_WAIT_L(0); PG8_BAR; PG8_MMA(0, 0, At, B0); PG8_MMA(0, 1, At, B1); PG8_BAR; PG8_SCHED;
	v_mfma_f32_16x16x32_bf16 v[62:65], v[130:133], v[186:189], 0
	v_mfma_f32_16x16x32_bf16 v[58:61], v[138:141], v[186:189], 0
	v_mfma_f32_16x16x32_bf16 v[54:57], v[130:133], v[198:201], 0
	v_mfma_f32_16x16x32_bf16 v[46:49], v[138:141], v[198:201], 0
	v_mfma_f32_16x16x32_bf16 v[38:41], v[130:133], v[206:209], 0
	v_mfma_f32_16x16x32_bf16 v[30:33], v[138:141], v[206:209], 0
	v_mfma_f32_16x16x32_bf16 v[22:25], v[130:133], v[224:227], 0
	v_mfma_f32_16x16x32_bf16 v[14:17], v[138:141], v[224:227], 0
	v_mfma_f32_16x16x32_bf16 v[62:65], v[134:137], v[194:197], v[62:65]
	v_mfma_f32_16x16x32_bf16 v[58:61], v[142:145], v[194:197], v[58:61]
	v_mfma_f32_16x16x32_bf16 v[54:57], v[134:137], v[202:205], v[54:57]
	v_mfma_f32_16x16x32_bf16 v[46:49], v[142:145], v[202:205], v[46:49]
	v_mfma_f32_16x16x32_bf16 v[38:41], v[134:137], v[220:223], v[38:41]
	v_mfma_f32_16x16x32_bf16 v[30:33], v[142:145], v[220:223], v[30:33]
	v_mfma_f32_16x16x32_bf16 v[22:25], v[134:137], v[228:231], v[22:25]
	v_mfma_f32_16x16x32_bf16 v[14:17], v[142:145], v[228:231], v[14:17]
	v_mfma_f32_16x16x32_bf16 v[50:53], v[146:149], v[186:189], 0
	v_mfma_f32_16x16x32_bf16 v[42:45], v[178:181], v[186:189], 0
	v_mfma_f32_16x16x32_bf16 v[34:37], v[146:149], v[198:201], 0
	v_mfma_f32_16x16x32_bf16 v[26:29], v[178:181], v[198:201], 0
	v_mfma_f32_16x16x32_bf16 v[18:21], v[146:149], v[206:209], 0
	v_mfma_f32_16x16x32_bf16 v[10:13], v[178:181], v[206:209], 0
	v_mfma_f32_16x16x32_bf16 v[6:9], v[146:149], v[224:227], 0
	v_mfma_f32_16x16x32_bf16 v[2:5], v[178:181], v[224:227], 0
	v_mfma_f32_16x16x32_bf16 v[50:53], v[150:153], v[194:197], v[50:53]
	v_mfma_f32_16x16x32_bf16 v[42:45], v[182:185], v[194:197], v[42:45]
	v_mfma_f32_16x16x32_bf16 v[34:37], v[150:153], v[202:205], v[34:37]
	v_mfma_f32_16x16x32_bf16 v[26:29], v[182:185], v[202:205], v[26:29]
	v_mfma_f32_16x16x32_bf16 v[18:21], v[150:153], v[220:223], v[18:21]
	v_mfma_f32_16x16x32_bf16 v[10:13], v[182:185], v[220:223], v[10:13]
	v_mfma_f32_16x16x32_bf16 v[6:9], v[150:153], v[228:231], v[6:9]
	v_mfma_f32_16x16x32_bf16 v[2:5], v[182:185], v[228:231], v[2:5]
	s_barrier
	s_add_i32 s17, 0, 0x18000
	s_add_i32 s23, 0, 0x1c000
	v_add_u32_e32 v142, s17, v190
	v_add_u32_e32 v182, s23, v190
	ds_read_b128 v[130:133], v142
	ds_read_b128 v[134:137], v142 offset:1024
	ds_read_b128 v[138:141], v142 offset:2048
	ds_read_b128 v[142:145], v142 offset:3072
	ds_read_b128 v[146:149], v182
	ds_read_b128 v[150:153], v182 offset:1024
	ds_read_b128 v[178:181], v182 offset:2048
	ds_read_b128 v[182:185], v182 offset:3072
	s_add_u32 s28, s28, 0x100000
	s_addc_u32 s29, s29, 0
	s_mov_b32 m0, s5
	v_lshl_add_u64 v[236:237], s[28:29], 0, v[154:155]
	ds_read_b128 v[186:189], v192 offset:32768
	ds_read_b128 v[194:197], v192 offset:33792
	ds_read_b128 v[198:201], v192 offset:34816
	ds_read_b128 v[202:205], v192 offset:35840
	ds_read_b128 v[206:209], v192 offset:36864
	ds_read_b128 v[220:223], v192 offset:37888
	ds_read_b128 v[224:227], v192 offset:38912
	ds_read_b128 v[228:231], v192 offset:39936
	global_load_lds_dwordx4 v[236:237], off
	v_lshl_add_u64 v[236:237], s[28:29], 0, v[156:157]
	s_mov_b32 m0, s6
	s_nop 0
	global_load_lds_dwordx4 v[236:237], off
	s_waitcnt vmcnt(8)
	s_waitcnt lgkmcnt(0)
	s_barrier
	v_mfma_f32_16x16x32_bf16 v[126:129], v[130:133], v[186:189], v[126:129]
	v_mfma_f32_16x16x32_bf16 v[122:125], v[138:141], v[186:189], v[122:125]
	v_mfma_f32_16x16x32_bf16 v[118:121], v[130:133], v[198:201], v[118:121]
	v_mfma_f32_16x16x32_bf16 v[114:117], v[138:141], v[198:201], v[114:117]
	v_mfma_f32_16x16x32_bf16 v[102:105], v[130:133], v[206:209], v[102:105]
	v_mfma_f32_16x16x32_bf16 v[94:97], v[138:141], v[206:209], v[94:97]
	v_mfma_f32_16x16x32_bf16 v[86:89], v[130:133], v[224:227], v[86:89]
	v_mfma_f32_16x16x32_bf16 v[78:81], v[138:141], v[224:227], v[78:81]
	v_mfma_f32_16x16x32_bf16 v[126:129], v[134:137], v[194:197], v[126:129]
	v_mfma_f32_16x16x32_bf16 v[122:125], v[142:145], v[194:197], v[122:125]
	v_mfma_f32_16x16x32_bf16 v[118:121], v[134:137], v[202:205], v[118:121]
	v_mfma_f32_16x16x32_bf16 v[114:117], v[142:145], v[202:205], v[114:117]
	v_mfma_f32_16x16x32_bf16 v[102:105], v[134:137], v[220:223], v[102:105]
	v_mfma_f32_16x16x32_bf16 v[94:97], v[142:145], v[220:223], v[94:97]
	v_mfma_f32_16x16x32_bf16 v[86:89], v[134:137], v[228:231], v[86:89]
	v_mfma_f32_16x16x32_bf16 v[78:81], v[142:145], v[228:231], v[78:81]
	v_mfma_f32_16x16x32_bf16 v[110:113], v[146:149], v[186:189], v[110:113]
	v_mfma_f32_16x16x32_bf16 v[106:109], v[178:181], v[186:189], v[106:109]
	v_mfma_f32_16x16x32_bf16 v[98:101], v[146:149], v[198:201], v[98:101]
	v_mfma_f32_16x16x32_bf16 v[90:93], v[178:181], v[198:201], v[90:93]
	v_mfma_f32_16x16x32_bf16 v[82:85], v[146:149], v[206:209], v[82:85]
	v_mfma_f32_16x16x32_bf16 v[74:77], v[178:181], v[206:209], v[74:77]
	v_mfma_f32_16x16x32_bf16 v[70:73], v[146:149], v[224:227], v[70:73]
	v_mfma_f32_16x16x32_bf16 v[66:69], v[178:181], v[224:227], v[66:69]
	v_mfma_f32_16x16x32_bf16 v[110:113], v[150:153], v[194:197], v[110:113]
	v_mfma_f32_16x16x32_bf16 v[106:109], v[182:185], v[194:197], v[106:109]
	v_mfma_f32_16x16x32_bf16 v[98:101], v[150:153], v[202:205], v[98:101]
	v_mfma_f32_16x16x32_bf16 v[90:93], v[182:185], v[202:205], v[90:93]
	v_mfma_f32_16x16x32_bf16 v[82:85], v[150:153], v[220:223], v[82:85]
	v_mfma_f32_16x16x32_bf16 v[74:77], v[182:185], v[220:223], v[74:77]
	v_mfma_f32_16x16x32_bf16 v[70:73], v[150:153], v[228:231], v[70:73]
	v_mfma_f32_16x16x32_bf16 v[66:69], v[182:185], v[228:231], v[66:69]
	s_barrier
; #define PG8_STAGE(bufoff, gbase, voff) do { _Pragma("unroll") for (int _i = 0; _i < 2; ++_i) \
;         __builtin_amdgcn_global_load_lds((const unsigned*)((const char*)(gbase) + (voff)[_i]), (PG8_LAS unsigned*)(lds + (bufoff) + ldsw + _i * 8192), 16, 0, 0); } while (0)
; #define PG8_LDA(dst, b, h) do { _Pragma("unroll") for (int m = 0; m < 4; ++m) _Pragma("unroll") for (int k = 0; k < 2; ++k) dst[m][k] = *(const PG8_LAS bf16x8*)(lds + PG8_SA(b, h) + aoff + m * 2048 + k * 1024); } while (0)
; #define PG8_MMA(ai, bj, At, Bt) do { __builtin_amdgcn_s_setprio(1); _Pragma("unroll") for (int m = 0; m < 4; ++m) _Pragma("unroll") for (int n = 0; n < 2; ++n) _Pragma("unroll") for (int k = 0; k < 2; ++k) \
;         acc[ai][bj][m][n] = __builtin_amdgcn_mfma_f32_16x16x32_bf16(Bt[n][k], At[m][k], acc[ai][bj][m][n], 0, 0, 0); __builtin_amdgcn_s_setprio(0); } while (0)
; #define PG8_WAIT_V(n) asm volatile("s_waitcnt vmcnt(" #n ")" ::: "memory")
; #define PG8_WAIT_L(n) asm volatile("s_waitcnt lgkmcnt(" #n ")" ::: "memory")
; #define PG8_BAR __builtin_amdgcn_s_barrier()
; #define PG8_SCHED __builtin_amdgcn_sched_barrier(0)
; template <class Epi, class Sched, bool ALIGN_EPI = false, bool SP2 = false>
; __device__ __forceinline__ void gemm_phase(PG8_LAS unsigned char* lds, const Gemm g, const Sched& S, const Epi& E) {
;     ...
;         for (int t = 0; t < nt; t += 2) {
;     ...
;             PG8_LDA(At, 1, 1); PG8_STAGE(PG8_SB(1, 0), b3, voffB); PG8_STAGE(PG8_SB(1, 1), b3 + hstep, voffB); PG8_STAGE(PG8_SA(1, 0), a3, voffA);
;             PG8_WAIT_V(8); PG8_WAIT_L(0); PG8_BAR; PG8_MMA(1, 0, At, B0); PG8_MMA(1, 1, At, B1); PG8_BAR; PG8_SCHED;
	s_add_i32 s17, s17, s34
	v_lshl_add_u64 v[170:171], v[170:171], 0, s[96:97]
	s_mov_b32 m0, s17
	ds_read_b128 v[186:189], v192 offset:49152
	ds_read_b128 v[194:197], v192 offset:50176
	ds_read_b128 v[198:201], v192 offset:51200
	ds_read_b128 v[202:205], v192 offset:52224
	ds_read_b128 v[206:209], v192 offset:53248
	ds_read_b128 v[220:223], v192 offset:54272
	ds_read_b128 v[224:227], v192 offset:55296
	ds_read_b128 v[228:231], v192 offset:56320
	global_load_lds_dwordx4 v[170:171], off
	s_add_i32 m0, s17, 0x2000
	s_add_u32 s26, s26, 0x100080
	v_lshl_add_u64 v[170:171], v[210:211], 0, s[96:97]
	s_addc_u32 s27, s27, 0
	s_add_i32 s17, s23, s34
	global_load_lds_dwordx4 v[170:171], off
	v_lshl_add_u64 v[170:171], s[26:27], 0, v[158:159]
	s_mov_b32 m0, s17
	s_nop 0
	global_load_lds_dwordx4 v[170:171], off
	v_lshl_add_u64 v[170:171], s[26:27], 0, v[172:173]
	s_add_i32 m0, s17, 0x2000
	s_nop 0
	global_load_lds_dwordx4 v[170:171], off
	v_lshl_add_u64 v[170:171], v[232:233], 0, s[96:97]
	s_mov_b32 m0, s9
	s_nop 0
	global_load_lds_dwordx4 v[170:171], off
	v_lshl_add_u64 v[170:171], v[234:235], 0, s[96:97]
	s_mov_b32 m0, s10
	s_nop 0
	global_load_lds_dwordx4 v[170:171], off
	s_waitcnt vmcnt(8)
	s_waitcnt lgkmcnt(0)
	s_barrier
	v_mfma_f32_16x16x32_bf16 v[62:65], v[130:133], v[186:189], v[62:65]
	v_mfma_f32_16x16x32_bf16 v[58:61], v[138:141], v[186:189], v[58:61]
	v_mfma_f32_16x16x32_bf16 v[54:57], v[130:133], v[198:201], v[54:57]
	v_mfma_f32_16x16x32_bf16 v[46:49], v[138:141], v[198:201], v[46:49]
	v_mfma_f32_16x16x32_bf16 v[38:41], v[130:133], v[206:209], v[38:41]
	v_mfma_f32_16x16x32_bf16 v[30:33], v[138:141], v[206:209], v[30:33]
	v_mfma_f32_16x16x32_bf16 v[22:25], v[130:133], v[224:227], v[22:25]
	v_mfma_f32_16x16x32_bf16 v[14:17], v[138:141], v[224:227], v[14:17]
	v_mfma_f32_16x16x32_bf16 v[62:65], v[134:137], v[194:197], v[62:65]
	v_mfma_f32_16x16x32_bf16 v[58:61], v[142:145], v[194:197], v[58:61]
	v_mfma_f32_16x16x32_bf16 v[54:57], v[134:137], v[202:205], v[54:57]
	v_mfma_f32_16x16x32_bf16 v[46:49], v[142:145], v[202:205], v[46:49]
	v_mfma_f32_16x16x32_bf16 v[38:41], v[134:137], v[220:223], v[38:41]
	v_mfma_f32_16x16x32_bf16 v[30:33], v[142:145], v[220:223], v[30:33]
	v_mfma_f32_16x16x32_bf16 v[22:25], v[134:137], v[228:231], v[22:25]
	v_mfma_f32_16x16x32_bf16 v[14:17], v[142:145], v[228:231], v[14:17]
	v_mfma_f32_16x16x32_bf16 v[50:53], v[146:149], v[186:189], v[50:53]
	v_mfma_f32_16x16x32_bf16 v[42:45], v[178:181], v[186:189], v[42:45]
	v_mfma_f32_16x16x32_bf16 v[34:37], v[146:149], v[198:201], v[34:37]
	v_mfma_f32_16x16x32_bf16 v[26:29], v[178:181], v[198:201], v[26:29]
	v_mfma_f32_16x16x32_bf16 v[18:21], v[146:149], v[206:209], v[18:21]
	v_mfma_f32_16x16x32_bf16 v[10:13], v[178:181], v[206:209], v[10:13]
	v_mfma_f32_16x16x32_bf16 v[6:9], v[146:149], v[224:227], v[6:9]
	v_mfma_f32_16x16x32_bf16 v[2:5], v[178:181], v[224:227], v[2:5]
	v_mfma_f32_16x16x32_bf16 v[50:53], v[150:153], v[194:197], v[50:53]
	v_mfma_f32_16x16x32_bf16 v[42:45], v[182:185], v[194:197], v[42:45]
	v_mfma_f32_16x16x32_bf16 v[34:37], v[150:153], v[202:205], v[34:37]
	v_mfma_f32_16x16x32_bf16 v[26:29], v[182:185], v[202:205], v[26:29]
	v_mfma_f32_16x16x32_bf16 v[18:21], v[150:153], v[220:223], v[18:21]
	v_mfma_f32_16x16x32_bf16 v[10:13], v[182:185], v[220:223], v[10:13]
	v_mfma_f32_16x16x32_bf16 v[6:9], v[150:153], v[228:231], v[6:9]
	v_mfma_f32_16x16x32_bf16 v[2:5], v[182:185], v[228:231], v[2:5]
	s_barrier
	s_add_u32 s15, s15, 0x100
	s_addc_u32 s16, s16, 0
	s_add_u32 s24, s24, 0x100
	s_addc_u32 s25, s25, 0
	s_cmp_ge_i32 s21, s13
	s_mov_b32 s17, s21
	s_cbranch_scc1 .Lpeel_exit_2

; #define PG8_STAGE(bufoff, gbase, voff) do { _Pragma("unroll") for (int _i = 0; _i < 2; ++_i) \
;         __builtin_amdgcn_global_load_lds((const unsigned*)((const char*)(gbase) + (voff)[_i]), (PG8_LAS unsigned*)(lds + (bufoff) + ldsw + _i * 8192), 16, 0, 0); } while (0)
; #define PG8_LDA(dst, b, h) do { _Pragma("unroll") for (int m = 0; m < 4; ++m) _Pragma("unroll") for (int k = 0; k < 2; ++k) dst[m][k] = *(const PG8_LAS bf16x8*)(lds + PG8_SA(b, h) + aoff + m * 2048 + k * 1024); } while (0)
; #define PG8_LDB(dst, b, h) do { _Pragma("unroll") for (int n = 0; n < 2; ++n) _Pragma("unroll") for (int k = 0; k < 2; ++k) dst[n][k] = *(const PG8_LAS bf16x8*)(lds + PG8_SB(b, h) + boff + n * 2048 + k * 1024); } while (0)
; #define PG8_MMA(ai, bj, At, Bt) do { __builtin_amdgcn_s_setprio(1); _Pragma("unroll") for (int m = 0; m < 4; ++m) _Pragma("unroll") for (int n = 0; n < 2; ++n) _Pragma("unroll") for (int k = 0; k < 2; ++k) \
;         acc[ai][bj][m][n] = __builtin_amdgcn_mfma_f32_16x16x32_bf16(Bt[n][k], At[m][k], acc[ai][bj][m][n], 0, 0, 0); __builtin_amdgcn_s_setprio(0); } while (0)
; template <class Epi, class Sched, bool ALIGN_EPI = false, bool SP2 = false>
; __device__ __forceinline__ void gemm_phase(PG8_LAS unsigned char* lds, const Gemm g, const Sched& S, const Epi& E) {
;     ...
;         const char* nA = has_next ? (const char*)g.A + (size_t)nxt.pm * tstep + (size_t)nxt.k0 * kstep : cA; const char* nB = has_next ? (const char*)g.Bt + (size_t)nxt.pn * tstep + (size_t)nxt.k0 * kstep : cB;
;         const int nt = cur.nt;
;         for (int t = 0; t < nt; t += 2) {
;             const bool last = (t == nt - 2);
;             const char* a1 = cA + (size_t)(t + 1) * kstep;
;             const char* a2 = last ? nA : cA + (size_t)(t + 2) * kstep; const char* b2 = last ? nB : cB + (size_t)(t + 2) * kstep;
;             const char* a3 = a2 + kstep; const char* b3 = b2 + kstep;
;             if (last && has_next) S.a_ready(nxt);
;             if constexpr (SP2) {
;             PG8_LDB(B0, 0, 0); PG8_LDB(B1, 0, 1); PG8_SCHED; PG8_LDA(At, 0, 0); PG8_STAGE(PG8_SA(1, 1), a1 + hstep, voffA);
;             PG8_WAIT_V(8); PG8_WAIT_L(0); PG8_BAR; PG8_MMA(0, 0, At, B0); PG8_MMA(0, 1, At, B1); PG8_BAR; PG8_SCHED;
;             PG8_LDA(At, 0, 1); PG8_STAGE(PG8_SB(0, 0), b2, voffB); PG8_STAGE(PG8_SB(0, 1), b2 + hstep, voffB); PG8_STAGE(PG8_SA(0, 0), a2, voffA);
.Lrb_skip_3:
	s_add_u32 s22, vcc_lo, 0xfff00080
	s_addc_u32 s23, vcc_hi, -1
	s_add_i32 s68, 0, 0x10000
	s_cmp_eq_u32 s65, 60
	s_cselect_b32 s25, s30, s23
	s_cselect_b32 s24, s31, s22
	s_cselect_b32 s23, s61, s17
	s_cselect_b32 s22, s63, s16
	s_add_i32 s70, 0, 0x14000
	v_add_u32_e32 v70, s68, v220
	v_add_u32_e32 v170, s70, v220
	ds_read_b128 v[50:53], v70
	ds_read_b128 v[54:57], v70 offset:1024
	ds_read_b128 v[66:69], v70 offset:2048
	ds_read_b128 v[70:73], v70 offset:3072
	ds_read_b128 v[74:77], v170
	ds_read_b128 v[86:89], v170 offset:1024
	ds_read_b128 v[154:157], v170 offset:2048
	ds_read_b128 v[188:191], v170 offset:3072
	v_lshl_add_u64 v[170:171], vcc, 0, v[186:187]
	s_add_i32 m0, s10, 0xc000
	ds_read_b128 v[192:195], v222
	ds_read_b128 v[196:199], v222 offset:1024
	ds_read_b128 v[200:203], v222 offset:2048
	ds_read_b128 v[204:207], v222 offset:3072
	ds_read_b128 v[224:227], v222 offset:4096
	ds_read_b128 v[228:231], v222 offset:5120
	ds_read_b128 v[232:235], v222 offset:6144
	ds_read_b128 v[236:239], v222 offset:7168
	global_load_lds_dwordx4 v[170:171], off
	v_lshl_add_u64 v[170:171], vcc, 0, v[184:185]
	s_add_i32 m0, s10, 0xe000
	s_nop 0
	global_load_lds_dwordx4 v[170:171], off
	s_waitcnt vmcnt(8)
	s_waitcnt lgkmcnt(0)
	s_barrier
	v_mfma_f32_16x16x32_bf16 v[142:145], v[50:53], v[192:195], 0
	v_mfma_f32_16x16x32_bf16 v[130:133], v[66:69], v[192:195], 0
	v_mfma_f32_16x16x32_bf16 v[138:141], v[50:53], v[200:203], 0
	v_mfma_f32_16x16x32_bf16 v[126:129], v[66:69], v[200:203], 0
	v_mfma_f32_16x16x32_bf16 v[118:121], v[50:53], v[224:227], 0
	v_mfma_f32_16x16x32_bf16 v[110:113], v[66:69], v[224:227], 0
	v_mfma_f32_16x16x32_bf16 v[98:101], v[50:53], v[232:235], 0
	v_mfma_f32_16x16x32_bf16 v[94:97], v[66:69], v[232:235], 0
	v_mfma_f32_16x16x32_bf16 v[142:145], v[54:57], v[196:199], v[142:145]
	v_mfma_f32_16x16x32_bf16 v[130:133], v[70:73], v[196:199], v[130:133]
	v_mfma_f32_16x16x32_bf16 v[138:141], v[54:57], v[204:207], v[138:141]
	v_mfma_f32_16x16x32_bf16 v[126:129], v[70:73], v[204:207], v[126:129]
	v_mfma_f32_16x16x32_bf16 v[118:121], v[54:57], v[228:231], v[118:121]
	v_mfma_f32_16x16x32_bf16 v[110:113], v[70:73], v[228:231], v[110:113]
	v_mfma_f32_16x16x32_bf16 v[98:101], v[54:57], v[236:239], v[98:101]
	v_mfma_f32_16x16x32_bf16 v[94:97], v[70:73], v[236:239], v[94:97]
	v_mfma_f32_16x16x32_bf16 v[150:153], v[74:77], v[192:195], 0
	v_mfma_f32_16x16x32_bf16 v[146:149], v[154:157], v[192:195], 0
	v_mfma_f32_16x16x32_bf16 v[134:137], v[74:77], v[200:203], 0
	v_mfma_f32_16x16x32_bf16 v[122:125], v[154:157], v[200:203], 0
	v_mfma_f32_16x16x32_bf16 v[114:117], v[74:77], v[224:227], 0
	v_mfma_f32_16x16x32_bf16 v[106:109], v[154:157], v[224:227], 0
	v_mfma_f32_16x16x32_bf16 v[102:105], v[74:77], v[232:235], 0
	v_mfma_f32_16x16x32_bf16 v[90:93], v[154:157], v[232:235], 0
	v_mfma_f32_16x16x32_bf16 v[150:153], v[86:89], v[196:199], v[150:153]
	v_mfma_f32_16x16x32_bf16 v[146:149], v[188:191], v[196:199], v[146:149]
	v_mfma_f32_16x16x32_bf16 v[134:137], v[86:89], v[204:207], v[134:137]
	v_mfma_f32_16x16x32_bf16 v[122:125], v[188:191], v[204:207], v[122:125]
	v_mfma_f32_16x16x32_bf16 v[114:117], v[86:89], v[228:231], v[114:117]
	v_mfma_f32_16x16x32_bf16 v[106:109], v[188:191], v[228:231], v[106:109]
	v_mfma_f32_16x16x32_bf16 v[102:105], v[86:89], v[236:239], v[102:105]
	v_mfma_f32_16x16x32_bf16 v[90:93], v[188:191], v[236:239], v[90:93]
	s_barrier
	s_add_i32 s68, s68, s9
	v_lshl_add_u64 v[170:171], s[22:23], 0, v[158:159]
	s_mov_b32 m0, s68
	ds_read_b128 v[192:195], v222 offset:16384
	ds_read_b128 v[196:199], v222 offset:17408
	ds_read_b128 v[200:203], v222 offset:18432
	ds_read_b128 v[204:207], v222 offset:19456
	ds_read_b128 v[224:227], v222 offset:20480
	ds_read_b128 v[228:231], v222 offset:21504
	ds_read_b128 v[232:235], v222 offset:22528
	ds_read_b128 v[236:239], v222 offset:23552
	global_load_lds_dwordx4 v[170:171], off
	s_add_i32 m0, s68, 0x2000
	s_add_u32 s68, s22, 0x100000
	v_lshl_add_u64 v[208:209], s[22:23], 0, v[172:173]
	s_addc_u32 s69, s23, 0
	s_add_i32 s70, s70, s9
	global_load_lds_dwordx4 v[208:209], off
	v_lshl_add_u64 v[210:211], s[68:69], 0, v[158:159]
	s_mov_b32 m0, s70
	v_lshl_add_u64 v[244:245], s[24:25], 0, v[174:175]
	global_load_lds_dwordx4 v[210:211], off
	v_lshl_add_u64 v[210:211], s[68:69], 0, v[172:173]
	s_add_i32 m0, s70, 0x2000
	s_nop 0
	global_load_lds_dwordx4 v[210:211], off
	v_lshl_add_u64 v[210:211], s[24:25], 0, v[176:177]
	s_mov_b32 m0, s10
	s_nop 0
	global_load_lds_dwordx4 v[210:211], off
	s_mov_b32 m0, s11
	s_nop 0
	global_load_lds_dwordx4 v[244:245], off
	s_waitcnt vmcnt(8)
	s_waitcnt lgkmcnt(0)
	s_barrier
; #define PG8_STAGE(bufoff, gbase, voff) do { _Pragma("unroll") for (int _i = 0; _i < 2; ++_i) \
;         __builtin_amdgcn_global_load_lds((const unsigned*)((const char*)(gbase) + (voff)[_i]), (PG8_LAS unsigned*)(lds + (bufoff) + ldsw + _i * 8192), 16, 0, 0); } while (0)
; #define PG8_LDA(dst, b, h) do { _Pragma("unroll") for (int m = 0; m < 4; ++m) _Pragma("unroll") for (int k = 0; k < 2; ++k) dst[m][k] = *(const PG8_LAS bf16x8*)(lds + PG8_SA(b, h) + aoff + m * 2048 + k * 1024); } while (0)
; #define PG8_LDB(dst, b, h) do { _Pragma("unroll") for (int n = 0; n < 2; ++n) _Pragma("unroll") for (int k = 0; k < 2; ++k) dst[n][k] = *(const PG8_LAS bf16x8*)(lds + PG8_SB(b, h) + boff + n * 2048 + k * 1024); } while (0)
; #define PG8_MMA(ai, bj, At, Bt) do { __builtin_amdgcn_s_setprio(1); _Pragma("unroll") for (int m = 0; m < 4; ++m) _Pragma("unroll") for (int n = 0; n < 2; ++n) _Pragma("unroll") for (int k = 0; k < 2; ++k) \
;         acc[ai][bj][m][n] = __builtin_amdgcn_mfma_f32_16x16x32_bf16(Bt[n][k], At[m][k], acc[ai][bj][m][n], 0, 0, 0); __builtin_amdgcn_s_setprio(0); } while (0)
; #define PG8_WAIT_V(n) asm volatile("s_waitcnt vmcnt(" #n ")" ::: "memory")
; #define PG8_WAIT_L(n) asm volatile("s_waitcnt lgkmcnt(" #n ")" ::: "memory")
; #define PG8_BAR __builtin_amdgcn_s_barrier()
; #define PG8_SCHED __builtin_amdgcn_sched_barrier(0)
; template <class Epi, class Sched, bool ALIGN_EPI = false, bool SP2 = false>
; __device__ __forceinline__ void gemm_phase(PG8_LAS unsigned char* lds, const Gemm g, const Sched& S, const Epi& E) {
;     ...
;             PG8_WAIT_V(8); PG8_WAIT_L(0); PG8_BAR; PG8_MMA(1, 0, At, B0); PG8_MMA(1, 1, At, B1); PG8_BAR; PG8_SCHED;
;             PG8_LDB(B0, 1, 0); PG8_LDB(B1, 1, 1); PG8_SCHED; PG8_LDA(At, 1, 0); PG8_STAGE(PG8_SA(0, 1), a2 + hstep, voffA);
;             PG8_WAIT_V(8); PG8_WAIT_L(0); PG8_BAR; PG8_MMA(0, 0, At, B0); PG8_MMA(0, 1, At, B1); PG8_BAR; PG8_SCHED;
	v_mfma_f32_16x16x32_bf16 v[62:65], v[50:53], v[192:195], 0
	v_mfma_f32_16x16x32_bf16 v[42:45], v[66:69], v[192:195], 0
	v_mfma_f32_16x16x32_bf16 v[58:61], v[50:53], v[200:203], 0
	v_mfma_f32_16x16x32_bf16 v[38:41], v[66:69], v[200:203], 0
	v_mfma_f32_16x16x32_bf16 v[30:33], v[50:53], v[224:227], 0
	v_mfma_f32_16x16x32_bf16 v[22:25], v[66:69], v[224:227], 0
	v_mfma_f32_16x16x32_bf16 v[10:13], v[50:53], v[232:235], 0
	v_mfma_f32_16x16x32_bf16 v[6:9], v[66:69], v[232:235], 0
	v_mfma_f32_16x16x32_bf16 v[62:65], v[54:57], v[196:199], v[62:65]
	v_mfma_f32_16x16x32_bf16 v[42:45], v[70:73], v[196:199], v[42:45]
	v_mfma_f32_16x16x32_bf16 v[58:61], v[54:57], v[204:207], v[58:61]
	v_mfma_f32_16x16x32_bf16 v[38:41], v[70:73], v[204:207], v[38:41]
	v_mfma_f32_16x16x32_bf16 v[30:33], v[54:57], v[228:231], v[30:33]
	v_mfma_f32_16x16x32_bf16 v[22:25], v[70:73], v[228:231], v[22:25]
	v_mfma_f32_16x16x32_bf16 v[10:13], v[54:57], v[236:239], v[10:13]
	v_mfma_f32_16x16x32_bf16 v[6:9], v[70:73], v[236:239], v[6:9]
	v_mfma_f32_16x16x32_bf16 v[46:49], v[74:77], v[200:203], 0
	v_mfma_f32_16x16x32_bf16 v[34:37], v[154:157], v[200:203], 0
	v_mfma_f32_16x16x32_bf16 v[26:29], v[74:77], v[224:227], 0
	v_mfma_f32_16x16x32_bf16 v[18:21], v[154:157], v[224:227], 0
	v_mfma_f32_16x16x32_bf16 v[14:17], v[74:77], v[232:235], 0
	v_mfma_f32_16x16x32_bf16 v[2:5], v[154:157], v[232:235], 0
	v_mfma_f32_16x16x32_bf16 v[50:53], v[74:77], v[192:195], 0
	v_mfma_f32_16x16x32_bf16 v[54:57], v[154:157], v[192:195], 0
	v_mfma_f32_16x16x32_bf16 v[46:49], v[86:89], v[204:207], v[46:49]
	v_mfma_f32_16x16x32_bf16 v[34:37], v[188:191], v[204:207], v[34:37]
	v_mfma_f32_16x16x32_bf16 v[26:29], v[86:89], v[228:231], v[26:29]
	v_mfma_f32_16x16x32_bf16 v[18:21], v[188:191], v[228:231], v[18:21]
	v_mfma_f32_16x16x32_bf16 v[14:17], v[86:89], v[236:239], v[14:17]
	v_mfma_f32_16x16x32_bf16 v[2:5], v[188:191], v[236:239], v[2:5]
	v_mfma_f32_16x16x32_bf16 v[50:53], v[86:89], v[196:199], v[50:53]
	v_mfma_f32_16x16x32_bf16 v[54:57], v[188:191], v[196:199], v[54:57]
	s_barrier
	s_add_i32 s68, 0, 0x18000
	s_add_i32 s69, 0, 0x1c000
	v_add_u32_e32 v78, s68, v220
	v_add_u32_e32 v82, s69, v220
	ds_read_b128 v[66:69], v78
	ds_read_b128 v[70:73], v78 offset:1024
	ds_read_b128 v[74:77], v78 offset:2048
	ds_read_b128 v[78:81], v78 offset:3072
	ds_read_b128 v[86:89], v82
	ds_read_b128 v[154:157], v82 offset:1024
	ds_read_b128 v[188:191], v82 offset:2048
	ds_read_b128 v[192:195], v82 offset:3072
	s_add_u32 s24, s24, 0x100000
	s_addc_u32 s25, s25, 0
	s_mov_b32 m0, s12
	v_lshl_add_u64 v[240:241], s[24:25], 0, v[176:177]
	ds_read_b128 v[82:85], v222 offset:32768
	ds_read_b128 v[196:199], v222 offset:33792
	ds_read_b128 v[200:203], v222 offset:34816
	ds_read_b128 v[204:207], v222 offset:35840
	ds_read_b128 v[224:227], v222 offset:36864
	ds_read_b128 v[228:231], v222 offset:37888
	ds_read_b128 v[232:235], v222 offset:38912
	ds_read_b128 v[236:239], v222 offset:39936
	global_load_lds_dwordx4 v[240:241], off
	v_lshl_add_u64 v[240:241], s[24:25], 0, v[174:175]
	s_mov_b32 m0, s13
	s_nop 0
	global_load_lds_dwordx4 v[240:241], off
	s_waitcnt vmcnt(8)
	s_waitcnt lgkmcnt(0)
	s_barrier
	v_mfma_f32_16x16x32_bf16 v[142:145], v[66:69], v[82:85], v[142:145]
	v_mfma_f32_16x16x32_bf16 v[130:133], v[74:77], v[82:85], v[130:133]
	v_mfma_f32_16x16x32_bf16 v[138:141], v[66:69], v[200:203], v[138:141]
	v_mfma_f32_16x16x32_bf16 v[126:129], v[74:77], v[200:203], v[126:129]
	v_mfma_f32_16x16x32_bf16 v[118:121], v[66:69], v[224:227], v[118:121]
	v_mfma_f32_16x16x32_bf16 v[110:113], v[74:77], v[224:227], v[110:113]
	v_mfma_f32_16x16x32_bf16 v[98:101], v[66:69], v[232:235], v[98:101]
	v_mfma_f32_16x16x32_bf16 v[94:97], v[74:77], v[232:235], v[94:97]
	v_mfma_f32_16x16x32_bf16 v[142:145], v[70:73], v[196:199], v[142:145]
	v_mfma_f32_16x16x32_bf16 v[130:133], v[78:81], v[196:199], v[130:133]
	v_mfma_f32_16x16x32_bf16 v[138:141], v[70:73], v[204:207], v[138:141]
	v_mfma_f32_16x16x32_bf16 v[126:129], v[78:81], v[204:207], v[126:129]
	v_mfma_f32_16x16x32_bf16 v[118:121], v[70:73], v[228:231], v[118:121]
	v_mfma_f32_16x16x32_bf16 v[110:113], v[78:81], v[228:231], v[110:113]
	v_mfma_f32_16x16x32_bf16 v[98:101], v[70:73], v[236:239], v[98:101]
	v_mfma_f32_16x16x32_bf16 v[94:97], v[78:81], v[236:239], v[94:97]
	v_mfma_f32_16x16x32_bf16 v[150:153], v[86:89], v[82:85], v[150:153]
	v_mfma_f32_16x16x32_bf16 v[146:149], v[188:191], v[82:85], v[146:149]
	v_mfma_f32_16x16x32_bf16 v[134:137], v[86:89], v[200:203], v[134:137]
	v_mfma_f32_16x16x32_bf16 v[122:125], v[188:191], v[200:203], v[122:125]
	v_mfma_f32_16x16x32_bf16 v[114:117], v[86:89], v[224:227], v[114:117]
	v_mfma_f32_16x16x32_bf16 v[106:109], v[188:191], v[224:227], v[106:109]
	v_mfma_f32_16x16x32_bf16 v[102:105], v[86:89], v[232:235], v[102:105]
	v_mfma_f32_16x16x32_bf16 v[90:93], v[188:191], v[232:235], v[90:93]
	v_mfma_f32_16x16x32_bf16 v[150:153], v[154:157], v[196:199], v[150:153]
	v_mfma_f32_16x16x32_bf16 v[146:149], v[192:195], v[196:199], v[146:149]
	v_mfma_f32_16x16x32_bf16 v[134:137], v[154:157], v[204:207], v[134:137]
	v_mfma_f32_16x16x32_bf16 v[122:125], v[192:195], v[204:207], v[122:125]
	v_mfma_f32_16x16x32_bf16 v[114:117], v[154:157], v[228:231], v[114:117]
	v_mfma_f32_16x16x32_bf16 v[106:109], v[192:195], v[228:231], v[106:109]
	v_mfma_f32_16x16x32_bf16 v[102:105], v[154:157], v[236:239], v[102:105]
	v_mfma_f32_16x16x32_bf16 v[90:93], v[192:195], v[236:239], v[90:93]
	s_barrier
; #define PG8_STAGE(bufoff, gbase, voff) do { _Pragma("unroll") for (int _i = 0; _i < 2; ++_i) \
;         __builtin_amdgcn_global_load_lds((const unsigned*)((const char*)(gbase) + (voff)[_i]), (PG8_LAS unsigned*)(lds + (bufoff) + ldsw + _i * 8192), 16, 0, 0); } while (0)
; #define PG8_LDA(dst, b, h) do { _Pragma("unroll") for (int m = 0; m < 4; ++m) _Pragma("unroll") for (int k = 0; k < 2; ++k) dst[m][k] = *(const PG8_LAS bf16x8*)(lds + PG8_SA(b, h) + aoff + m * 2048 + k * 1024); } while (0)
; #define PG8_MMA(ai, bj, At, Bt) do { __builtin_amdgcn_s_setprio(1); _Pragma("unroll") for (int m = 0; m < 4; ++m) _Pragma("unroll") for (int n = 0; n < 2; ++n) _Pragma("unroll") for (int k = 0; k < 2; ++k) \
;         acc[ai][bj][m][n] = __builtin_amdgcn_mfma_f32_16x16x32_bf16(Bt[n][k], At[m][k], acc[ai][bj][m][n], 0, 0, 0); __builtin_amdgcn_s_setprio(0); } while (0)
; #define PG8_WAIT_V(n) asm volatile("s_waitcnt vmcnt(" #n ")" ::: "memory")
; #define PG8_WAIT_L(n) asm volatile("s_waitcnt lgkmcnt(" #n ")" ::: "memory")
; #define PG8_BAR __builtin_amdgcn_s_barrier()
; #define PG8_SCHED __builtin_amdgcn_sched_barrier(0)
; template <class Epi, class Sched, bool ALIGN_EPI = false, bool SP2 = false>
; __device__ __forceinline__ void gemm_phase(PG8_LAS unsigned char* lds, const Gemm g, const Sched& S, const Epi& E) {
;     ...
;         for (int t = 0; t < nt; t += 2) {
;     ...
;             PG8_LDA(At, 1, 1); PG8_STAGE(PG8_SB(1, 0), b3, voffB); PG8_STAGE(PG8_SB(1, 1), b3 + hstep, voffB); PG8_STAGE(PG8_SA(1, 0), a3, voffA);
;             PG8_WAIT_V(8); PG8_WAIT_L(0); PG8_BAR; PG8_MMA(1, 0, At, B0); PG8_MMA(1, 1, At, B1); PG8_BAR; PG8_SCHED;
	s_add_i32 s24, s68, s9
	s_nop 2
	v_lshl_add_u64 v[82:83], v[170:171], 0, s[96:97]
	s_mov_b32 m0, s24
	ds_read_b128 v[196:199], v222 offset:49152
	ds_read_b128 v[200:203], v222 offset:50176
	ds_read_b128 v[204:207], v222 offset:51200
	ds_read_b128 v[224:227], v222 offset:52224
	ds_read_b128 v[228:231], v222 offset:53248
	ds_read_b128 v[232:235], v222 offset:54272
	ds_read_b128 v[236:239], v222 offset:55296
	ds_read_b128 v[240:243], v222 offset:56320
	global_load_lds_dwordx4 v[82:83], off
	s_add_i32 m0, s24, 0x2000
	s_add_u32 s22, s22, 0x100080
	v_lshl_add_u64 v[82:83], v[208:209], 0, s[96:97]
	s_addc_u32 s23, s23, 0
	s_add_i32 s24, s69, s9
	global_load_lds_dwordx4 v[82:83], off
	v_lshl_add_u64 v[82:83], s[22:23], 0, v[158:159]
	s_mov_b32 m0, s24
	s_nop 0
	global_load_lds_dwordx4 v[82:83], off
	v_lshl_add_u64 v[82:83], s[22:23], 0, v[172:173]
	s_add_i32 m0, s24, 0x2000
	s_nop 0
	global_load_lds_dwordx4 v[82:83], off
	v_lshl_add_u64 v[82:83], v[210:211], 0, s[96:97]
	s_mov_b32 m0, s0
	s_nop 0
	global_load_lds_dwordx4 v[82:83], off
	v_lshl_add_u64 v[82:83], v[244:245], 0, s[96:97]
	s_mov_b32 m0, s34
	s_nop 0
	global_load_lds_dwordx4 v[82:83], off
	s_waitcnt vmcnt(8)
	s_waitcnt lgkmcnt(0)
	s_barrier
	v_mfma_f32_16x16x32_bf16 v[62:65], v[66:69], v[196:199], v[62:65]
	v_mfma_f32_16x16x32_bf16 v[42:45], v[74:77], v[196:199], v[42:45]
	v_mfma_f32_16x16x32_bf16 v[58:61], v[66:69], v[204:207], v[58:61]
	v_mfma_f32_16x16x32_bf16 v[38:41], v[74:77], v[204:207], v[38:41]
	v_mfma_f32_16x16x32_bf16 v[30:33], v[66:69], v[228:231], v[30:33]
	v_mfma_f32_16x16x32_bf16 v[22:25], v[74:77], v[228:231], v[22:25]
	v_mfma_f32_16x16x32_bf16 v[10:13], v[66:69], v[236:239], v[10:13]
	v_mfma_f32_16x16x32_bf16 v[6:9], v[74:77], v[236:239], v[6:9]
	v_mfma_f32_16x16x32_bf16 v[62:65], v[70:73], v[200:203], v[62:65]
	v_mfma_f32_16x16x32_bf16 v[42:45], v[78:81], v[200:203], v[42:45]
	v_mfma_f32_16x16x32_bf16 v[58:61], v[70:73], v[224:227], v[58:61]
	v_mfma_f32_16x16x32_bf16 v[38:41], v[78:81], v[224:227], v[38:41]
	v_mfma_f32_16x16x32_bf16 v[30:33], v[70:73], v[232:235], v[30:33]
	v_mfma_f32_16x16x32_bf16 v[22:25], v[78:81], v[232:235], v[22:25]
	v_mfma_f32_16x16x32_bf16 v[10:13], v[70:73], v[240:243], v[10:13]
	v_mfma_f32_16x16x32_bf16 v[6:9], v[78:81], v[240:243], v[6:9]
	v_mfma_f32_16x16x32_bf16 v[50:53], v[86:89], v[196:199], v[50:53]
	v_mfma_f32_16x16x32_bf16 v[54:57], v[188:191], v[196:199], v[54:57]
	v_mfma_f32_16x16x32_bf16 v[46:49], v[86:89], v[204:207], v[46:49]
	v_mfma_f32_16x16x32_bf16 v[34:37], v[188:191], v[204:207], v[34:37]
	v_mfma_f32_16x16x32_bf16 v[26:29], v[86:89], v[228:231], v[26:29]
	v_mfma_f32_16x16x32_bf16 v[18:21], v[188:191], v[228:231], v[18:21]
	v_mfma_f32_16x16x32_bf16 v[14:17], v[86:89], v[236:239], v[14:17]
	v_mfma_f32_16x16x32_bf16 v[2:5], v[188:191], v[236:239], v[2:5]
	v_mfma_f32_16x16x32_bf16 v[82:85], v[154:157], v[200:203], v[50:53]
	v_mfma_f32_16x16x32_bf16 v[78:81], v[192:195], v[200:203], v[54:57]
	v_mfma_f32_16x16x32_bf16 v[46:49], v[154:157], v[224:227], v[46:49]
	v_mfma_f32_16x16x32_bf16 v[34:37], v[192:195], v[224:227], v[34:37]
	v_mfma_f32_16x16x32_bf16 v[26:29], v[154:157], v[232:235], v[26:29]
	v_mfma_f32_16x16x32_bf16 v[18:21], v[192:195], v[232:235], v[18:21]
	v_mfma_f32_16x16x32_bf16 v[14:17], v[154:157], v[240:243], v[14:17]
	v_mfma_f32_16x16x32_bf16 v[2:5], v[192:195], v[240:243], v[2:5]
	s_barrier
	s_add_i32 s65, s65, 2
	s_add_u32 s16, s16, 0x100
	s_addc_u32 s17, s17, 0
	s_add_u32 vcc_lo, vcc_lo, 0x100
	s_addc_u32 vcc_hi, vcc_hi, 0
	s_cmp_gt_u32 s65, 61
	s_cbranch_scc1 .Lpeel_exit_3

; #define PG8_STAGE(bufoff, gbase, voff) do { _Pragma("unroll") for (int _i = 0; _i < 2; ++_i) \
;         __builtin_amdgcn_global_load_lds((const unsigned*)((const char*)(gbase) + (voff)[_i]), (PG8_LAS unsigned*)(lds + (bufoff) + ldsw + _i * 8192), 16, 0, 0); } while (0)
; #define PG8_LDA(dst, b, h) do { _Pragma("unroll") for (int m = 0; m < 4; ++m) _Pragma("unroll") for (int k = 0; k < 2; ++k) dst[m][k] = *(const PG8_LAS bf16x8*)(lds + PG8_SA(b, h) + aoff + m * 2048 + k * 1024); } while (0)
; #define PG8_LDB(dst, b, h) do { _Pragma("unroll") for (int n = 0; n < 2; ++n) _Pragma("unroll") for (int k = 0; k < 2; ++k) dst[n][k] = *(const PG8_LAS bf16x8*)(lds + PG8_SB(b, h) + boff + n * 2048 + k * 1024); } while (0)
; #define PG8_MMA(ai, bj, At, Bt) do { __builtin_amdgcn_s_setprio(1); _Pragma("unroll") for (int m = 0; m < 4; ++m) _Pragma("unroll") for (int n = 0; n < 2; ++n) _Pragma("unroll") for (int k = 0; k < 2; ++k) \
;         acc[ai][bj][m][n] = __builtin_amdgcn_mfma_f32_16x16x32_bf16(Bt[n][k], At[m][k], acc[ai][bj][m][n], 0, 0, 0); __builtin_amdgcn_s_setprio(0); } while (0)
; #define PG8_WAIT_V(n) asm volatile("s_waitcnt vmcnt(" #n ")" ::: "memory")
; #define PG8_WAIT_L(n) asm volatile("s_waitcnt lgkmcnt(" #n ")" ::: "memory")
; #define PG8_BAR __builtin_amdgcn_s_barrier()
; #define PG8_SCHED __builtin_amdgcn_sched_barrier(0)
; template <class Epi, class Sched, bool ALIGN_EPI = false, bool SP2 = false>
; __device__ __forceinline__ void gemm_phase(PG8_LAS unsigned char* lds, const Gemm g, const Sched& S, const Epi& E) {
;     ...
;             const bool last = (t == nt - 2);
;             const char* a1 = cA + (size_t)(t + 1) * kstep;
;             const char* a2 = last ? nA : cA + (size_t)(t + 2) * kstep; const char* b2 = last ? nB : cB + (size_t)(t + 2) * kstep;
;             const char* a3 = a2 + kstep; const char* b3 = b2 + kstep;
;             if (last && has_next) S.a_ready(nxt);
;             if constexpr (SP2) {
;             PG8_LDB(B0, 0, 0); PG8_LDB(B1, 0, 1); PG8_SCHED; PG8_LDA(At, 0, 0); PG8_STAGE(PG8_SA(1, 1), a1 + hstep, voffA);
;             PG8_WAIT_V(8); PG8_WAIT_L(0); PG8_BAR; PG8_MMA(0, 0, At, B0); PG8_MMA(0, 1, At, B1); PG8_BAR; PG8_SCHED;
;             PG8_LDA(At, 0, 1); PG8_STAGE(PG8_SB(0, 0), b2, voffB); PG8_STAGE(PG8_SB(0, 1), b2 + hstep, voffB); PG8_STAGE(PG8_SA(0, 0), a2, voffA);
.Lrb_skip_4:
	s_add_i32 s30, s28, 2
	s_add_u32 s26, s48, 0x100
	s_addc_u32 s27, s49, 0
	s_add_i32 s43, 0, 0x10000
	s_cmp_eq_u32 s15, s28
	s_cselect_b32 s51, s45, s27
	s_cselect_b32 s50, s44, s26
	s_cselect_b32 s29, s47, s17
	s_cselect_b32 s28, s46, s16
	s_add_i32 s59, 0, 0x14000
	v_add_u32_e32 v142, s43, v188
	v_add_u32_e32 v170, s59, v188
	ds_read_b128 v[130:133], v142
	ds_read_b128 v[134:137], v142 offset:1024
	ds_read_b128 v[138:141], v142 offset:2048
	ds_read_b128 v[142:145], v142 offset:3072
	ds_read_b128 v[146:149], v170
	ds_read_b128 v[150:153], v170 offset:1024
	ds_read_b128 v[178:181], v170 offset:2048
	ds_read_b128 v[182:185], v170 offset:3072
	v_lshl_add_u64 v[170:171], s[48:49], 0, v[176:177]
	s_add_i32 m0, s9, 0xc000
	ds_read_b128 v[192:195], v190
	ds_read_b128 v[196:199], v190 offset:1024
	ds_read_b128 v[200:203], v190 offset:2048
	ds_read_b128 v[204:207], v190 offset:3072
	ds_read_b128 v[220:223], v190 offset:4096
	ds_read_b128 v[224:227], v190 offset:5120
	ds_read_b128 v[228:231], v190 offset:6144
	ds_read_b128 v[232:235], v190 offset:7168
	global_load_lds_dwordx4 v[170:171], off
	v_lshl_add_u64 v[170:171], s[48:49], 0, v[174:175]
	s_add_i32 m0, s9, 0xe000
	s_nop 0
	global_load_lds_dwordx4 v[170:171], off
	s_waitcnt vmcnt(8)
	s_waitcnt lgkmcnt(0)
	s_barrier
	v_mfma_f32_16x16x32_bf16 v[126:129], v[130:133], v[192:195], 0
	v_mfma_f32_16x16x32_bf16 v[122:125], v[138:141], v[192:195], 0
	v_mfma_f32_16x16x32_bf16 v[118:121], v[130:133], v[200:203], 0
	v_mfma_f32_16x16x32_bf16 v[114:117], v[138:141], v[200:203], 0
	v_mfma_f32_16x16x32_bf16 v[102:105], v[130:133], v[220:223], 0
	v_mfma_f32_16x16x32_bf16 v[94:97], v[138:141], v[220:223], 0
	v_mfma_f32_16x16x32_bf16 v[86:89], v[130:133], v[228:231], 0
	v_mfma_f32_16x16x32_bf16 v[78:81], v[138:141], v[228:231], 0
	v_mfma_f32_16x16x32_bf16 v[126:129], v[134:137], v[196:199], v[126:129]
	v_mfma_f32_16x16x32_bf16 v[122:125], v[142:145], v[196:199], v[122:125]
	v_mfma_f32_16x16x32_bf16 v[118:121], v[134:137], v[204:207], v[118:121]
	v_mfma_f32_16x16x32_bf16 v[114:117], v[142:145], v[204:207], v[114:117]
	v_mfma_f32_16x16x32_bf16 v[102:105], v[134:137], v[224:227], v[102:105]
	v_mfma_f32_16x16x32_bf16 v[94:97], v[142:145], v[224:227], v[94:97]
	v_mfma_f32_16x16x32_bf16 v[86:89], v[134:137], v[232:235], v[86:89]
	v_mfma_f32_16x16x32_bf16 v[78:81], v[142:145], v[232:235], v[78:81]
	v_mfma_f32_16x16x32_bf16 v[110:113], v[146:149], v[192:195], 0
	v_mfma_f32_16x16x32_bf16 v[106:109], v[178:181], v[192:195], 0
	v_mfma_f32_16x16x32_bf16 v[98:101], v[146:149], v[200:203], 0
	v_mfma_f32_16x16x32_bf16 v[90:93], v[178:181], v[200:203], 0
	v_mfma_f32_16x16x32_bf16 v[82:85], v[146:149], v[220:223], 0
	v_mfma_f32_16x16x32_bf16 v[74:77], v[178:181], v[220:223], 0
	v_mfma_f32_16x16x32_bf16 v[70:73], v[146:149], v[228:231], 0
	v_mfma_f32_16x16x32_bf16 v[66:69], v[178:181], v[228:231], 0
	v_mfma_f32_16x16x32_bf16 v[110:113], v[150:153], v[196:199], v[110:113]
	v_mfma_f32_16x16x32_bf16 v[106:109], v[182:185], v[196:199], v[106:109]
	v_mfma_f32_16x16x32_bf16 v[98:101], v[150:153], v[204:207], v[98:101]
	v_mfma_f32_16x16x32_bf16 v[90:93], v[182:185], v[204:207], v[90:93]
	v_mfma_f32_16x16x32_bf16 v[82:85], v[150:153], v[224:227], v[82:85]
	v_mfma_f32_16x16x32_bf16 v[74:77], v[182:185], v[224:227], v[74:77]
	v_mfma_f32_16x16x32_bf16 v[70:73], v[150:153], v[232:235], v[70:73]
	v_mfma_f32_16x16x32_bf16 v[66:69], v[182:185], v[232:235], v[66:69]
	s_barrier
	s_add_i32 s43, s43, s8
	v_lshl_add_u64 v[170:171], s[28:29], 0, v[158:159]
	s_mov_b32 m0, s43
	ds_read_b128 v[192:195], v190 offset:16384
	ds_read_b128 v[196:199], v190 offset:17408
	ds_read_b128 v[200:203], v190 offset:18432
	ds_read_b128 v[204:207], v190 offset:19456
	ds_read_b128 v[220:223], v190 offset:20480
	ds_read_b128 v[224:227], v190 offset:21504
	ds_read_b128 v[228:231], v190 offset:22528
	ds_read_b128 v[232:235], v190 offset:23552
	global_load_lds_dwordx4 v[170:171], off
	s_add_i32 m0, s43, 0x2000
	s_add_u32 s48, s28, 0x2b0000
	v_lshl_add_u64 v[186:187], s[28:29], 0, v[172:173]
	s_addc_u32 s49, s29, 0
	s_add_i32 s43, s59, s8
	global_load_lds_dwordx4 v[186:187], off
	v_lshl_add_u64 v[208:209], s[48:49], 0, v[158:159]
	s_mov_b32 m0, s43
	v_lshl_add_u64 v[210:211], s[50:51], 0, v[156:157]
	global_load_lds_dwordx4 v[208:209], off
	v_lshl_add_u64 v[208:209], s[48:49], 0, v[172:173]
	s_add_i32 m0, s43, 0x2000
	s_nop 0
	global_load_lds_dwordx4 v[208:209], off
	v_lshl_add_u64 v[208:209], s[50:51], 0, v[154:155]
	s_mov_b32 m0, s9
	s_nop 0
	global_load_lds_dwordx4 v[208:209], off
	s_mov_b32 m0, s10
	s_nop 0
	global_load_lds_dwordx4 v[210:211], off
	s_waitcnt vmcnt(8)
	s_waitcnt lgkmcnt(0)
	s_barrier
; #define PG8_STAGE(bufoff, gbase, voff) do { _Pragma("unroll") for (int _i = 0; _i < 2; ++_i) \
;         __builtin_amdgcn_global_load_lds((const unsigned*)((const char*)(gbase) + (voff)[_i]), (PG8_LAS unsigned*)(lds + (bufoff) + ldsw + _i * 8192), 16, 0, 0); } while (0)
; #define PG8_LDA(dst, b, h) do { _Pragma("unroll") for (int m = 0; m < 4; ++m) _Pragma("unroll") for (int k = 0; k < 2; ++k) dst[m][k] = *(const PG8_LAS bf16x8*)(lds + PG8_SA(b, h) + aoff + m * 2048 + k * 1024); } while (0)
; #define PG8_LDB(dst, b, h) do { _Pragma("unroll") for (int n = 0; n < 2; ++n) _Pragma("unroll") for (int k = 0; k < 2; ++k) dst[n][k] = *(const PG8_LAS bf16x8*)(lds + PG8_SB(b, h) + boff + n * 2048 + k * 1024); } while (0)
; #define PG8_MMA(ai, bj, At, Bt) do { __builtin_amdgcn_s_setprio(1); _Pragma("unroll") for (int m = 0; m < 4; ++m) _Pragma("unroll") for (int n = 0; n < 2; ++n) _Pragma("unroll") for (int k = 0; k < 2; ++k) \
;         acc[ai][bj][m][n] = __builtin_amdgcn_mfma_f32_16x16x32_bf16(Bt[n][k], At[m][k], acc[ai][bj][m][n], 0, 0, 0); __builtin_amdgcn_s_setprio(0); } while (0)
; #define PG8_WAIT_V(n) asm volatile("s_waitcnt vmcnt(" #n ")" ::: "memory")
; #define PG8_WAIT_L(n) asm volatile("s_waitcnt lgkmcnt(" #n ")" ::: "memory")
; #define PG8_BAR __builtin_amdgcn_s_barrier()
; #define PG8_SCHED __builtin_amdgcn_sched_barrier(0)
; template <class Epi, class Sched, bool ALIGN_EPI = false, bool SP2 = false>
; __device__ __forceinline__ void gemm_phase(PG8_LAS unsigned char* lds, const Gemm g, const Sched& S, const Epi& E) {
;     ...
;             PG8_WAIT_V(8); PG8_WAIT_L(0); PG8_BAR; PG8_MMA(1, 0, At, B0); PG8_MMA(1, 1, At, B1); PG8_BAR; PG8_SCHED;
;             PG8_LDB(B0, 1, 0); PG8_LDB(B1, 1, 1); PG8_SCHED; PG8_LDA(At, 1, 0); PG8_STAGE(PG8_SA(0, 1), a2 + hstep, voffA);
;             PG8_WAIT_V(8); PG8_WAIT_L(0); PG8_BAR; PG8_MMA(0, 0, At, B0); PG8_MMA(0, 1, At, B1); PG8_BAR; PG8_SCHED;
	v_mfma_f32_16x16x32_bf16 v[62:65], v[130:133], v[192:195], 0
	v_mfma_f32_16x16x32_bf16 v[58:61], v[138:141], v[192:195], 0
	v_mfma_f32_16x16x32_bf16 v[54:57], v[130:133], v[200:203], 0
	v_mfma_f32_16x16x32_bf16 v[46:49], v[138:141], v[200:203], 0
	v_mfma_f32_16x16x32_bf16 v[38:41], v[130:133], v[220:223], 0
	v_mfma_f32_16x16x32_bf16 v[30:33], v[138:141], v[220:223], 0
	v_mfma_f32_16x16x32_bf16 v[22:25], v[130:133], v[228:231], 0
	v_mfma_f32_16x16x32_bf16 v[14:17], v[138:141], v[228:231], 0
	v_mfma_f32_16x16x32_bf16 v[62:65], v[134:137], v[196:199], v[62:65]
	v_mfma_f32_16x16x32_bf16 v[58:61], v[142:145], v[196:199], v[58:61]
	v_mfma_f32_16x16x32_bf16 v[54:57], v[134:137], v[204:207], v[54:57]
	v_mfma_f32_16x16x32_bf16 v[46:49], v[142:145], v[204:207], v[46:49]
	v_mfma_f32_16x16x32_bf16 v[38:41], v[134:137], v[224:227], v[38:41]
	v_mfma_f32_16x16x32_bf16 v[30:33], v[142:145], v[224:227], v[30:33]
	v_mfma_f32_16x16x32_bf16 v[22:25], v[134:137], v[232:235], v[22:25]
	v_mfma_f32_16x16x32_bf16 v[14:17], v[142:145], v[232:235], v[14:17]
	v_mfma_f32_16x16x32_bf16 v[50:53], v[146:149], v[192:195], 0
	v_mfma_f32_16x16x32_bf16 v[42:45], v[178:181], v[192:195], 0
	v_mfma_f32_16x16x32_bf16 v[34:37], v[146:149], v[200:203], 0
	v_mfma_f32_16x16x32_bf16 v[26:29], v[178:181], v[200:203], 0
	v_mfma_f32_16x16x32_bf16 v[18:21], v[146:149], v[220:223], 0
	v_mfma_f32_16x16x32_bf16 v[10:13], v[178:181], v[220:223], 0
	v_mfma_f32_16x16x32_bf16 v[6:9], v[146:149], v[228:231], 0
	v_mfma_f32_16x16x32_bf16 v[2:5], v[178:181], v[228:231], 0
	v_mfma_f32_16x16x32_bf16 v[50:53], v[150:153], v[196:199], v[50:53]
	v_mfma_f32_16x16x32_bf16 v[42:45], v[182:185], v[196:199], v[42:45]
	v_mfma_f32_16x16x32_bf16 v[34:37], v[150:153], v[204:207], v[34:37]
	v_mfma_f32_16x16x32_bf16 v[26:29], v[182:185], v[204:207], v[26:29]
	v_mfma_f32_16x16x32_bf16 v[18:21], v[150:153], v[224:227], v[18:21]
	v_mfma_f32_16x16x32_bf16 v[10:13], v[182:185], v[224:227], v[10:13]
	v_mfma_f32_16x16x32_bf16 v[6:9], v[150:153], v[232:235], v[6:9]
	v_mfma_f32_16x16x32_bf16 v[2:5], v[182:185], v[232:235], v[2:5]
	s_barrier
	s_add_i32 s43, 0, 0x18000
	s_add_i32 s59, 0, 0x1c000
	v_add_u32_e32 v142, s43, v188
	v_add_u32_e32 v182, s59, v188
	ds_read_b128 v[130:133], v142
	ds_read_b128 v[134:137], v142 offset:1024
	ds_read_b128 v[138:141], v142 offset:2048
	ds_read_b128 v[142:145], v142 offset:3072
	ds_read_b128 v[146:149], v182
	ds_read_b128 v[150:153], v182 offset:1024
	ds_read_b128 v[178:181], v182 offset:2048
	ds_read_b128 v[182:185], v182 offset:3072
	s_add_u32 s48, s50, 0x2b0000
	s_addc_u32 s49, s51, 0
	s_mov_b32 m0, s11
	v_lshl_add_u64 v[236:237], s[48:49], 0, v[154:155]
	ds_read_b128 v[192:195], v190 offset:32768
	ds_read_b128 v[196:199], v190 offset:33792
	ds_read_b128 v[200:203], v190 offset:34816
	ds_read_b128 v[204:207], v190 offset:35840
	ds_read_b128 v[220:223], v190 offset:36864
	ds_read_b128 v[224:227], v190 offset:37888
	ds_read_b128 v[228:231], v190 offset:38912
	ds_read_b128 v[232:235], v190 offset:39936
	global_load_lds_dwordx4 v[236:237], off
	v_lshl_add_u64 v[236:237], s[48:49], 0, v[156:157]
	s_mov_b32 m0, s12
	s_nop 0
	global_load_lds_dwordx4 v[236:237], off
	s_waitcnt vmcnt(8)
	s_waitcnt lgkmcnt(0)
	s_barrier
	v_mfma_f32_16x16x32_bf16 v[126:129], v[130:133], v[192:195], v[126:129]
	v_mfma_f32_16x16x32_bf16 v[122:125], v[138:141], v[192:195], v[122:125]
	v_mfma_f32_16x16x32_bf16 v[118:121], v[130:133], v[200:203], v[118:121]
	v_mfma_f32_16x16x32_bf16 v[114:117], v[138:141], v[200:203], v[114:117]
	v_mfma_f32_16x16x32_bf16 v[102:105], v[130:133], v[220:223], v[102:105]
	v_mfma_f32_16x16x32_bf16 v[94:97], v[138:141], v[220:223], v[94:97]
	v_mfma_f32_16x16x32_bf16 v[86:89], v[130:133], v[228:231], v[86:89]
	v_mfma_f32_16x16x32_bf16 v[78:81], v[138:141], v[228:231], v[78:81]
	v_mfma_f32_16x16x32_bf16 v[126:129], v[134:137], v[196:199], v[126:129]
	v_mfma_f32_16x16x32_bf16 v[122:125], v[142:145], v[196:199], v[122:125]
	v_mfma_f32_16x16x32_bf16 v[118:121], v[134:137], v[204:207], v[118:121]
	v_mfma_f32_16x16x32_bf16 v[114:117], v[142:145], v[204:207], v[114:117]
	v_mfma_f32_16x16x32_bf16 v[102:105], v[134:137], v[224:227], v[102:105]
	v_mfma_f32_16x16x32_bf16 v[94:97], v[142:145], v[224:227], v[94:97]
	v_mfma_f32_16x16x32_bf16 v[86:89], v[134:137], v[232:235], v[86:89]
	v_mfma_f32_16x16x32_bf16 v[78:81], v[142:145], v[232:235], v[78:81]
	v_mfma_f32_16x16x32_bf16 v[110:113], v[146:149], v[192:195], v[110:113]
	v_mfma_f32_16x16x32_bf16 v[106:109], v[178:181], v[192:195], v[106:109]
	v_mfma_f32_16x16x32_bf16 v[98:101], v[146:149], v[200:203], v[98:101]
	v_mfma_f32_16x16x32_bf16 v[90:93], v[178:181], v[200:203], v[90:93]
	v_mfma_f32_16x16x32_bf16 v[82:85], v[146:149], v[220:223], v[82:85]
	v_mfma_f32_16x16x32_bf16 v[74:77], v[178:181], v[220:223], v[74:77]
	v_mfma_f32_16x16x32_bf16 v[70:73], v[146:149], v[228:231], v[70:73]
	v_mfma_f32_16x16x32_bf16 v[66:69], v[178:181], v[228:231], v[66:69]
	v_mfma_f32_16x16x32_bf16 v[110:113], v[150:153], v[196:199], v[110:113]
	v_mfma_f32_16x16x32_bf16 v[106:109], v[182:185], v[196:199], v[106:109]
	v_mfma_f32_16x16x32_bf16 v[98:101], v[150:153], v[204:207], v[98:101]
	v_mfma_f32_16x16x32_bf16 v[90:93], v[182:185], v[204:207], v[90:93]
	v_mfma_f32_16x16x32_bf16 v[82:85], v[150:153], v[224:227], v[82:85]
	v_mfma_f32_16x16x32_bf16 v[74:77], v[182:185], v[224:227], v[74:77]
	v_mfma_f32_16x16x32_bf16 v[70:73], v[150:153], v[232:235], v[70:73]
	v_mfma_f32_16x16x32_bf16 v[66:69], v[182:185], v[232:235], v[66:69]
	s_barrier
; #define PG8_STAGE(bufoff, gbase, voff) do { _Pragma("unroll") for (int _i = 0; _i < 2; ++_i) \
;         __builtin_amdgcn_global_load_lds((const unsigned*)((const char*)(gbase) + (voff)[_i]), (PG8_LAS unsigned*)(lds + (bufoff) + ldsw + _i * 8192), 16, 0, 0); } while (0)
; #define PG8_LDA(dst, b, h) do { _Pragma("unroll") for (int m = 0; m < 4; ++m) _Pragma("unroll") for (int k = 0; k < 2; ++k) dst[m][k] = *(const PG8_LAS bf16x8*)(lds + PG8_SA(b, h) + aoff + m * 2048 + k * 1024); } while (0)
; #define PG8_MMA(ai, bj, At, Bt) do { __builtin_amdgcn_s_setprio(1); _Pragma("unroll") for (int m = 0; m < 4; ++m) _Pragma("unroll") for (int n = 0; n < 2; ++n) _Pragma("unroll") for (int k = 0; k < 2; ++k) \
;         acc[ai][bj][m][n] = __builtin_amdgcn_mfma_f32_16x16x32_bf16(Bt[n][k], At[m][k], acc[ai][bj][m][n], 0, 0, 0); __builtin_amdgcn_s_setprio(0); } while (0)
; #define PG8_WAIT_V(n) asm volatile("s_waitcnt vmcnt(" #n ")" ::: "memory")
; #define PG8_WAIT_L(n) asm volatile("s_waitcnt lgkmcnt(" #n ")" ::: "memory")
; #define PG8_BAR __builtin_amdgcn_s_barrier()
; #define PG8_SCHED __builtin_amdgcn_sched_barrier(0)
; template <class Epi, class Sched, bool ALIGN_EPI = false, bool SP2 = false>
; __device__ __forceinline__ void gemm_phase(PG8_LAS unsigned char* lds, const Gemm g, const Sched& S, const Epi& E) {
;     ...
;         for (int t = 0; t < nt; t += 2) {
;     ...
;             PG8_LDA(At, 1, 1); PG8_STAGE(PG8_SB(1, 0), b3, voffB); PG8_STAGE(PG8_SB(1, 1), b3 + hstep, voffB); PG8_STAGE(PG8_SA(1, 0), a3, voffA);
;             PG8_WAIT_V(8); PG8_WAIT_L(0); PG8_BAR; PG8_MMA(1, 0, At, B0); PG8_MMA(1, 1, At, B1); PG8_BAR; PG8_SCHED;
	s_add_i32 s43, s43, s8
	v_lshl_add_u64 v[170:171], v[170:171], 0, s[96:97]
	s_mov_b32 m0, s43
	ds_read_b128 v[192:195], v190 offset:49152
	ds_read_b128 v[196:199], v190 offset:50176
	ds_read_b128 v[200:203], v190 offset:51200
	ds_read_b128 v[204:207], v190 offset:52224
	ds_read_b128 v[220:223], v190 offset:53248
	ds_read_b128 v[224:227], v190 offset:54272
	ds_read_b128 v[228:231], v190 offset:55296
	ds_read_b128 v[232:235], v190 offset:56320
	global_load_lds_dwordx4 v[170:171], off
	s_add_i32 m0, s43, 0x2000
	s_add_u32 s28, s28, 0x2b0080
	v_lshl_add_u64 v[170:171], v[186:187], 0, s[96:97]
	s_addc_u32 s29, s29, 0
	s_add_i32 s43, s59, s8
	global_load_lds_dwordx4 v[170:171], off
	v_lshl_add_u64 v[170:171], s[28:29], 0, v[158:159]
	s_mov_b32 m0, s43
	s_nop 0
	global_load_lds_dwordx4 v[170:171], off
	v_lshl_add_u64 v[170:171], s[28:29], 0, v[172:173]
	s_add_i32 m0, s43, 0x2000
	s_nop 0
	global_load_lds_dwordx4 v[170:171], off
	v_lshl_add_u64 v[170:171], v[208:209], 0, s[96:97]
	s_mov_b32 m0, s35
	s_nop 0
	global_load_lds_dwordx4 v[170:171], off
	v_lshl_add_u64 v[170:171], v[210:211], 0, s[96:97]
	s_mov_b32 m0, s52
	s_nop 0
	global_load_lds_dwordx4 v[170:171], off
	s_waitcnt vmcnt(8)
	s_waitcnt lgkmcnt(0)
	s_barrier
	v_mfma_f32_16x16x32_bf16 v[62:65], v[130:133], v[192:195], v[62:65]
	v_mfma_f32_16x16x32_bf16 v[58:61], v[138:141], v[192:195], v[58:61]
	v_mfma_f32_16x16x32_bf16 v[54:57], v[130:133], v[200:203], v[54:57]
	v_mfma_f32_16x16x32_bf16 v[46:49], v[138:141], v[200:203], v[46:49]
	v_mfma_f32_16x16x32_bf16 v[38:41], v[130:133], v[220:223], v[38:41]
	v_mfma_f32_16x16x32_bf16 v[30:33], v[138:141], v[220:223], v[30:33]
	v_mfma_f32_16x16x32_bf16 v[22:25], v[130:133], v[228:231], v[22:25]
	v_mfma_f32_16x16x32_bf16 v[14:17], v[138:141], v[228:231], v[14:17]
	v_mfma_f32_16x16x32_bf16 v[62:65], v[134:137], v[196:199], v[62:65]
	v_mfma_f32_16x16x32_bf16 v[58:61], v[142:145], v[196:199], v[58:61]
	v_mfma_f32_16x16x32_bf16 v[54:57], v[134:137], v[204:207], v[54:57]
	v_mfma_f32_16x16x32_bf16 v[46:49], v[142:145], v[204:207], v[46:49]
	v_mfma_f32_16x16x32_bf16 v[38:41], v[134:137], v[224:227], v[38:41]
	v_mfma_f32_16x16x32_bf16 v[30:33], v[142:145], v[224:227], v[30:33]
	v_mfma_f32_16x16x32_bf16 v[22:25], v[134:137], v[232:235], v[22:25]
	v_mfma_f32_16x16x32_bf16 v[14:17], v[142:145], v[232:235], v[14:17]
	v_mfma_f32_16x16x32_bf16 v[50:53], v[146:149], v[192:195], v[50:53]
	v_mfma_f32_16x16x32_bf16 v[42:45], v[178:181], v[192:195], v[42:45]
	v_mfma_f32_16x16x32_bf16 v[34:37], v[146:149], v[200:203], v[34:37]
	v_mfma_f32_16x16x32_bf16 v[26:29], v[178:181], v[200:203], v[26:29]
	v_mfma_f32_16x16x32_bf16 v[18:21], v[146:149], v[220:223], v[18:21]
	v_mfma_f32_16x16x32_bf16 v[10:13], v[178:181], v[220:223], v[10:13]
	v_mfma_f32_16x16x32_bf16 v[6:9], v[146:149], v[228:231], v[6:9]
	v_mfma_f32_16x16x32_bf16 v[2:5], v[178:181], v[228:231], v[2:5]
	v_mfma_f32_16x16x32_bf16 v[50:53], v[150:153], v[196:199], v[50:53]
	v_mfma_f32_16x16x32_bf16 v[42:45], v[182:185], v[196:199], v[42:45]
	v_mfma_f32_16x16x32_bf16 v[34:37], v[150:153], v[204:207], v[34:37]
	v_mfma_f32_16x16x32_bf16 v[26:29], v[182:185], v[204:207], v[26:29]
	v_mfma_f32_16x16x32_bf16 v[18:21], v[150:153], v[224:227], v[18:21]
	v_mfma_f32_16x16x32_bf16 v[10:13], v[182:185], v[224:227], v[10:13]
	v_mfma_f32_16x16x32_bf16 v[6:9], v[150:153], v[232:235], v[6:9]
	v_mfma_f32_16x16x32_bf16 v[2:5], v[182:185], v[232:235], v[2:5]
	s_barrier
	s_add_u32 s16, s16, 0x100
	s_addc_u32 s17, s17, 0
	s_cmp_ge_i32 s30, s14
	s_mov_b64 s[48:49], s[26:27]
	s_mov_b32 s28, s30
	s_cbranch_scc1 .Lpeel_exit_4
